# software-pipelined the f32 mm64 LDS loops (DN1 x8, DN3 x1): next k-step operands prefetched into a second register set
# speedup vs baseline: 1.0128x; 1.0128x over previous
; __device__ __forceinline__ int tidx() { int t = threadIdx.x; asm volatile("" : "+v"(t)); return t; }
; __device__ __forceinline__ void dn3_item(const Params& p, int l, int item, unsigned char* lds) {
;     bf16_t* PB = (bf16_t*)(p.ws + OFF_PB);
;     const float* DNQ = (const float*)(p.ws + OFF_DNQ) + (size_t)item * 4096;
;     const float* DNS = (const float*)(p.ws + OFF_DNS) + (size_t)item * 4096;
;     const float* DNO = (const float*)(p.ws + OFF_DNO) + (size_t)item * 4096;
;     float* B0 = (float*)lds; float* B1 = B0 + 64 * DLD;
;     const int tid = tidx(), ty = tid >> 4, tx = tid & 15;
;     const int cchunk = item >> 3, hd = item & 7, t0 = cchunk * 64;
;     __syncthreads();
; #pragma unroll
;     for (int e = 0; e < 4; ++e) {
;         const int id = tid + 256 * e, row = id >> 4, c4 = (id & 15) * 4;
;         *(f32x4*)(B0 + row * DLD + c4) = *(const f32x4*)(DNQ + row * 64 + c4);
;         *(f32x4*)(B1 + row * DLD + c4) = *(const f32x4*)(DNS + row * 64 + c4);
;     }
;     __syncthreads();
;     float acc[4][4];
; #pragma unroll
;     for (int rr = 0; rr < 4; ++rr) { const f32x4 o = *(const f32x4*)(DNO + (4 * ty + rr) * 64 + 4 * tx); acc[rr][0] = o.x; acc[rr][1] = o.y; acc[rr][2] = o.z; acc[rr][3] = o.w; }
;     mm64(B0, B1, acc, ty, tx);
.LBB0_180:
	s_lshl_b32 s0, s7, 3
	s_add_i32 s0, s40, s0
	s_add_i32 s88, s0, 0xfffff800
	s_waitcnt vmcnt(45)
	v_mov_b32_e32 v20, v179
	s_lshl_b64 s[0:1], s[88:89], 14
	s_add_u32 s4, s37, s0
	v_ashrrev_i32_e32 v19, 4, v20
	v_lshlrev_b32_e32 v0, 2, v20
	v_and_b32_e32 v18, 60, v0
	v_lshlrev_b32_e32 v2, 6, v19
	s_addc_u32 s5, s56, s1
	v_lshlrev_b32_e32 v0, 2, v18
	v_ashrrev_i32_e32 v3, 31, v2
	v_lshl_add_u64 v[6:7], s[4:5], 0, v[0:1]
	v_lshlrev_b64 v[12:13], 2, v[2:3]
	v_lshl_add_u64 v[2:3], v[6:7], 0, v[12:13]
	s_barrier
	global_load_dwordx4 v[2:5], v[2:3], off
	s_add_u32 s8, s57, s0
	s_addc_u32 s9, s68, s1
	v_add_u32_e32 v8, 0, v0
	v_lshl_add_u64 v[10:11], s[8:9], 0, v[0:1]
	s_movk_i32 s8, 0x110
	v_mad_u64_u32 v[14:15], s[4:5], v19, s8, v[8:9]
	s_add_u32 s0, s69, s0
	s_addc_u32 s1, s70, s1
	s_waitcnt vmcnt(0)
	ds_write_b128 v14, v[2:5]
	v_lshl_add_u64 v[2:3], v[10:11], 0, v[12:13]
	global_load_dwordx4 v[2:5], v[2:3], off
	s_waitcnt vmcnt(0)
	ds_write_b128 v14, v[2:5] offset:17408
	v_add_u32_e32 v2, 0x100, v20
	v_ashrrev_i32_e32 v9, 4, v2
	v_lshlrev_b32_e32 v2, 6, v9
	v_ashrrev_i32_e32 v3, 31, v2
	v_lshlrev_b64 v[12:13], 2, v[2:3]
	v_lshl_add_u64 v[2:3], v[6:7], 0, v[12:13]
	global_load_dwordx4 v[2:5], v[2:3], off
	v_mad_u64_u32 v[14:15], s[4:5], v9, s8, v[8:9]
	s_waitcnt vmcnt(0)
	ds_write_b128 v14, v[2:5]
	v_lshl_add_u64 v[2:3], v[10:11], 0, v[12:13]
	global_load_dwordx4 v[2:5], v[2:3], off
	s_waitcnt vmcnt(0)
	ds_write_b128 v14, v[2:5] offset:17408
	v_add_u32_e32 v2, 0x200, v20
	v_ashrrev_i32_e32 v9, 4, v2
	v_lshlrev_b32_e32 v2, 6, v9
	v_ashrrev_i32_e32 v3, 31, v2
	v_lshlrev_b64 v[12:13], 2, v[2:3]
	v_lshl_add_u64 v[2:3], v[6:7], 0, v[12:13]
	global_load_dwordx4 v[2:5], v[2:3], off
	v_mad_u64_u32 v[14:15], s[4:5], v9, s8, v[8:9]
	s_waitcnt vmcnt(0)
	ds_write_b128 v14, v[2:5]
	v_lshl_add_u64 v[2:3], v[10:11], 0, v[12:13]
	global_load_dwordx4 v[2:5], v[2:3], off
	s_waitcnt vmcnt(0)
	ds_write_b128 v14, v[2:5] offset:17408
	v_add_u32_e32 v2, 0x300, v20
	v_ashrrev_i32_e32 v9, 4, v2
	v_lshlrev_b32_e32 v2, 6, v9
	v_ashrrev_i32_e32 v3, 31, v2
	v_lshlrev_b64 v[12:13], 2, v[2:3]
	v_lshl_add_u64 v[2:3], v[6:7], 0, v[12:13]
	global_load_dwordx4 v[2:5], v[2:3], off
	v_mad_u64_u32 v[6:7], s[4:5], v9, s8, v[8:9]
	s_waitcnt vmcnt(0)
	ds_write_b128 v6, v[2:5]
	v_lshl_add_u64 v[2:3], v[10:11], 0, v[12:13]
	global_load_dwordx4 v[2:5], v[2:3], off
	s_waitcnt vmcnt(0)
	ds_write_b128 v6, v[2:5] offset:17408
	v_lshlrev_b32_e32 v2, 8, v19
	v_lshl_add_u64 v[4:5], s[0:1], 0, v[0:1]
	v_ashrrev_i32_e32 v3, 31, v2
	v_lshl_add_u64 v[2:3], v[2:3], 2, v[4:5]
	s_waitcnt lgkmcnt(0)
	s_barrier
	global_load_dwordx4 v[14:17], v[2:3], off
	global_load_dwordx4 v[10:13], v[2:3], off offset:256
	global_load_dwordx4 v[6:9], v[2:3], off offset:512
	s_nop 0
	global_load_dwordx4 v[2:5], v[2:3], off offset:768
	v_lshlrev_b32_e32 v0, 2, v19
	v_and_b32_e32 v19, -16, v20
	v_and_b32_e32 v20, 15, v20
	v_readlane_b32 s0, v253, 47
	v_add_u32_e32 v19, 0, v19
	s_nop 0
	v_lshl_add_u32 v20, v20, 4, s0
	s_mov_b32 s0, 0
	v_add_u32_e32 v21, s0, v19
	v_add_u32_e32 v34, s0, v20
	ds_read_b128 v[22:25], v21
	ds_read_b128 v[26:29], v34
	s_waitcnt vmcnt(0)
.LBB0_181:
	ds_read_b128 v[238:241], v21 offset:272
	ds_read_b128 v[242:245], v34 offset:272
	s_waitcnt lgkmcnt(2)
	v_pk_fma_f32 v[14:15], v[22:23], v[26:27], v[14:15] op_sel_hi:[0,1,1]
	v_pk_fma_f32 v[16:17], v[22:23], v[28:29], v[16:17] op_sel_hi:[0,1,1]
	v_pk_fma_f32 v[10:11], v[22:23], v[26:27], v[10:11] op_sel:[1,0,0]
	v_pk_fma_f32 v[12:13], v[22:23], v[28:29], v[12:13] op_sel:[1,0,0]
	v_pk_fma_f32 v[6:7], v[24:25], v[26:27], v[6:7] op_sel_hi:[0,1,1]
	v_pk_fma_f32 v[8:9], v[24:25], v[28:29], v[8:9] op_sel_hi:[0,1,1]
	v_pk_fma_f32 v[2:3], v[24:25], v[26:27], v[2:3] op_sel:[1,0,0]
	v_pk_fma_f32 v[4:5], v[24:25], v[28:29], v[4:5] op_sel:[1,0,0]
	ds_read_b128 v[22:25], v21 offset:544
	ds_read_b128 v[26:29], v34 offset:544
	s_waitcnt lgkmcnt(2)
	v_pk_fma_f32 v[14:15], v[238:239], v[242:243], v[14:15] op_sel_hi:[0,1,1]
	v_pk_fma_f32 v[16:17], v[238:239], v[244:245], v[16:17] op_sel_hi:[0,1,1]
	v_pk_fma_f32 v[10:11], v[238:239], v[242:243], v[10:11] op_sel:[1,0,0]
	v_pk_fma_f32 v[12:13], v[238:239], v[244:245], v[12:13] op_sel:[1,0,0]
	v_pk_fma_f32 v[6:7], v[240:241], v[242:243], v[6:7] op_sel_hi:[0,1,1]
	v_pk_fma_f32 v[8:9], v[240:241], v[244:245], v[8:9] op_sel_hi:[0,1,1]
	v_pk_fma_f32 v[2:3], v[240:241], v[242:243], v[2:3] op_sel:[1,0,0]
	v_pk_fma_f32 v[4:5], v[240:241], v[244:245], v[4:5] op_sel:[1,0,0]
	ds_read_b128 v[238:241], v21 offset:816
	ds_read_b128 v[242:245], v34 offset:816
	s_waitcnt lgkmcnt(2)
	v_pk_fma_f32 v[14:15], v[22:23], v[26:27], v[14:15] op_sel_hi:[0,1,1]
	v_pk_fma_f32 v[16:17], v[22:23], v[28:29], v[16:17] op_sel_hi:[0,1,1]
	v_pk_fma_f32 v[10:11], v[22:23], v[26:27], v[10:11] op_sel:[1,0,0]
	v_pk_fma_f32 v[12:13], v[22:23], v[28:29], v[12:13] op_sel:[1,0,0]
	v_pk_fma_f32 v[6:7], v[24:25], v[26:27], v[6:7] op_sel_hi:[0,1,1]
	v_pk_fma_f32 v[8:9], v[24:25], v[28:29], v[8:9] op_sel_hi:[0,1,1]
	v_pk_fma_f32 v[2:3], v[24:25], v[26:27], v[2:3] op_sel:[1,0,0]
	v_pk_fma_f32 v[4:5], v[24:25], v[28:29], v[4:5] op_sel:[1,0,0]
	ds_read_b128 v[22:25], v21 offset:1088
	ds_read_b128 v[26:29], v34 offset:1088
	s_waitcnt lgkmcnt(2)
	v_pk_fma_f32 v[14:15], v[238:239], v[242:243], v[14:15] op_sel_hi:[0,1,1]
	v_pk_fma_f32 v[16:17], v[238:239], v[244:245], v[16:17] op_sel_hi:[0,1,1]
	v_pk_fma_f32 v[10:11], v[238:239], v[242:243], v[10:11] op_sel:[1,0,0]
	v_pk_fma_f32 v[12:13], v[238:239], v[244:245], v[12:13] op_sel:[1,0,0]
	v_pk_fma_f32 v[6:7], v[240:241], v[242:243], v[6:7] op_sel_hi:[0,1,1]
	v_pk_fma_f32 v[8:9], v[240:241], v[244:245], v[8:9] op_sel_hi:[0,1,1]
	v_pk_fma_f32 v[2:3], v[240:241], v[242:243], v[2:3] op_sel:[1,0,0]
	v_pk_fma_f32 v[4:5], v[240:241], v[244:245], v[4:5] op_sel:[1,0,0]
	ds_read_b128 v[238:241], v21 offset:1360
	ds_read_b128 v[242:245], v34 offset:1360
	s_waitcnt lgkmcnt(2)
; __device__ __forceinline__ void mm64(const float* At, const float* B, float (&acc)[4][4], int ty, int tx) {
;     ...
;     for (int k = 0; k < 64; ++k) {
;         const f32x4 a = *(const f32x4*)(At + k * DLD + 4 * ty);
;         const f32x4 b = *(const f32x4*)(B + k * DLD + 4 * tx);
;         const f32x2 b01 = {b.x, b.y}, b23 = {b.z, b.w};
; #pragma unroll
;         for (int rr = 0; rr < 4; ++rr) {
;             const f32x2 a2 = {a[rr], a[rr]};
;             c2[rr][0] = __builtin_elementwise_fma(a2, b01, c2[rr][0]);
;             c2[rr][1] = __builtin_elementwise_fma(a2, b23, c2[rr][1]);
;         }
;     }
; __device__ __forceinline__ void dn3_item(const Params& p, int l, int item, unsigned char* lds) {
;     ...
;     const f32x4 gn = *(const f32x4*)(p.dn_onorm + l * 64 + 4 * tx);
; #pragma unroll
;     for (int rr = 0; rr < 4; ++rr) {
;         float ss = acc[rr][0] * acc[rr][0] + acc[rr][1] * acc[rr][1] + acc[rr][2] * acc[rr][2] + acc[rr][3] * acc[rr][3];
;         ss += __shfl_xor(ss, 1); ss += __shfl_xor(ss, 2); ss += __shfl_xor(ss, 4); ss += __shfl_xor(ss, 8);
;         const float rs = rsqrtf(ss * (1.f / 64.f) + EPS);
	v_pk_fma_f32 v[14:15], v[22:23], v[26:27], v[14:15] op_sel_hi:[0,1,1]
	v_pk_fma_f32 v[16:17], v[22:23], v[28:29], v[16:17] op_sel_hi:[0,1,1]
	v_pk_fma_f32 v[10:11], v[22:23], v[26:27], v[10:11] op_sel:[1,0,0]
	v_pk_fma_f32 v[12:13], v[22:23], v[28:29], v[12:13] op_sel:[1,0,0]
	v_pk_fma_f32 v[6:7], v[24:25], v[26:27], v[6:7] op_sel_hi:[0,1,1]
	v_pk_fma_f32 v[8:9], v[24:25], v[28:29], v[8:9] op_sel_hi:[0,1,1]
	v_pk_fma_f32 v[2:3], v[24:25], v[26:27], v[2:3] op_sel:[1,0,0]
	v_pk_fma_f32 v[4:5], v[24:25], v[28:29], v[4:5] op_sel:[1,0,0]
	ds_read_b128 v[22:25], v21 offset:1632
	ds_read_b128 v[26:29], v34 offset:1632
	s_waitcnt lgkmcnt(2)
	v_pk_fma_f32 v[14:15], v[238:239], v[242:243], v[14:15] op_sel_hi:[0,1,1]
	v_pk_fma_f32 v[16:17], v[238:239], v[244:245], v[16:17] op_sel_hi:[0,1,1]
	v_pk_fma_f32 v[10:11], v[238:239], v[242:243], v[10:11] op_sel:[1,0,0]
	v_pk_fma_f32 v[12:13], v[238:239], v[244:245], v[12:13] op_sel:[1,0,0]
	v_pk_fma_f32 v[6:7], v[240:241], v[242:243], v[6:7] op_sel_hi:[0,1,1]
	v_pk_fma_f32 v[8:9], v[240:241], v[244:245], v[8:9] op_sel_hi:[0,1,1]
	v_pk_fma_f32 v[2:3], v[240:241], v[242:243], v[2:3] op_sel:[1,0,0]
	v_pk_fma_f32 v[4:5], v[240:241], v[244:245], v[4:5] op_sel:[1,0,0]
	ds_read_b128 v[238:241], v21 offset:1904
	ds_read_b128 v[242:245], v34 offset:1904
	s_waitcnt lgkmcnt(2)
	v_pk_fma_f32 v[14:15], v[22:23], v[26:27], v[14:15] op_sel_hi:[0,1,1]
	v_pk_fma_f32 v[16:17], v[22:23], v[28:29], v[16:17] op_sel_hi:[0,1,1]
	v_pk_fma_f32 v[10:11], v[22:23], v[26:27], v[10:11] op_sel:[1,0,0]
	v_pk_fma_f32 v[12:13], v[22:23], v[28:29], v[12:13] op_sel:[1,0,0]
	v_pk_fma_f32 v[6:7], v[24:25], v[26:27], v[6:7] op_sel_hi:[0,1,1]
	v_pk_fma_f32 v[8:9], v[24:25], v[28:29], v[8:9] op_sel_hi:[0,1,1]
	v_pk_fma_f32 v[2:3], v[24:25], v[26:27], v[2:3] op_sel:[1,0,0]
	v_pk_fma_f32 v[4:5], v[24:25], v[28:29], v[4:5] op_sel:[1,0,0]
	s_addk_i32 s0, 0x880
	v_add_u32_e32 v21, s0, v19
	v_add_u32_e32 v34, s0, v20
	ds_read_b128 v[22:25], v21
	ds_read_b128 v[26:29], v34
	s_waitcnt lgkmcnt(2)
	v_pk_fma_f32 v[14:15], v[238:239], v[242:243], v[14:15] op_sel_hi:[0,1,1]
	v_pk_fma_f32 v[16:17], v[238:239], v[244:245], v[16:17] op_sel_hi:[0,1,1]
	v_pk_fma_f32 v[10:11], v[238:239], v[242:243], v[10:11] op_sel:[1,0,0]
	v_pk_fma_f32 v[12:13], v[238:239], v[244:245], v[12:13] op_sel:[1,0,0]
	v_pk_fma_f32 v[6:7], v[240:241], v[242:243], v[6:7] op_sel_hi:[0,1,1]
	v_pk_fma_f32 v[8:9], v[240:241], v[244:245], v[8:9] op_sel_hi:[0,1,1]
	v_pk_fma_f32 v[2:3], v[240:241], v[242:243], v[2:3] op_sel:[1,0,0]
	v_pk_fma_f32 v[4:5], v[240:241], v[244:245], v[4:5] op_sel:[1,0,0]
	s_cmpk_lg_i32 s0, 0x4400
	s_cbranch_scc1 .LBB0_181
	s_waitcnt lgkmcnt(0)
	s_lshl_b32 s0, s88, 3
	s_and_b32 s0, s0, 0x3ffffc0
	v_add_u32_e32 v44, s0, v0
	s_lshl_b32 s0, s88, 7
	s_and_b32 s0, s0, 0x380
	s_add_u32 s0, s71, s0
	s_addc_u32 s1, s72, 0
	v_lshlrev_b32_e32 v0, 1, v18
	v_lshl_add_u64 v[30:31], s[0:1], 0, v[0:1]
	v_mad_i64_i32 v[24:25], s[0:1], v44, s60, v[30:31]
	global_load_dwordx2 v[26:27], v[24:25], off offset:3072
	v_lshlrev_b32_e32 v0, 2, v18
	v_and_b32_e32 v38, 64, v228
	v_pk_mul_f32 v[28:29], v[10:11], v[10:11]
	global_load_dwordx4 v[18:21], v0, s[24:25]
	v_pk_mul_f32 v[32:33], v[14:15], v[14:15]
	s_mov_b32 s0, 0x358637bd
	v_add_u32_e32 v0, 64, v38
	v_mov_b32_e32 v38, v28
	v_or_b32_e32 v28, 1, v44
	v_mov_b64_e32 v[22:23], s[0:1]
	v_mov_b32_e32 v39, v32
	v_mov_b32_e32 v32, v29
	v_mad_i64_i32 v[28:29], s[0:1], v28, s60, v[30:31]
	global_load_dwordx2 v[42:43], v[28:29], off offset:3072
	v_xor_b32_e32 v45, 1, v228
	v_xor_b32_e32 v46, 2, v228
	v_pk_mul_f32 v[36:37], v[12:13], v[12:13]
	v_cmp_lt_i32_e32 vcc, v45, v0
	v_xor_b32_e32 v47, 4, v228
	v_mov_b32_e32 v40, v36
	v_cndmask_b32_e32 v36, v228, v45, vcc
	v_cmp_lt_i32_e32 vcc, v46, v0
	v_xor_b32_e32 v48, 8, v228
	v_pk_mul_f32 v[34:35], v[16:17], v[16:17]
	v_lshlrev_b32_e32 v49, 2, v36
	v_cndmask_b32_e32 v36, v228, v46, vcc
	v_cmp_lt_i32_e32 vcc, v47, v0
	v_mov_b32_e32 v41, v34
	v_mov_b32_e32 v34, v37
	v_cndmask_b32_e32 v37, v228, v47, vcc
	v_cmp_lt_i32_e32 vcc, v48, v0
	v_pk_add_f32 v[32:33], v[38:39], v[32:33]
	v_lshlrev_b32_e32 v50, 2, v36
	v_cndmask_b32_e32 v0, v228, v48, vcc
	v_lshlrev_b32_e32 v51, 2, v0
	v_or_b32_e32 v0, 2, v44
	v_lshlrev_b32_e32 v48, 2, v37
	v_or_b32_e32 v38, 3, v44
	v_mad_i64_i32 v[36:37], s[0:1], v0, s60, v[30:31]
	v_pk_add_f32 v[32:33], v[40:41], v[32:33]
	v_mad_i64_i32 v[30:31], s[0:1], v38, s60, v[30:31]
	global_load_dwordx2 v[38:39], v[36:37], off offset:3072
	global_load_dwordx2 v[40:41], v[30:31], off offset:3072
	v_pk_add_f32 v[32:33], v[34:35], v[32:33]
	ds_bpermute_b32 v35, v49, v33
	ds_bpermute_b32 v34, v49, v32
	s_mov_b32 s4, 0x3c800000
	s_mov_b32 s0, 0x800000
	s_waitcnt lgkmcnt(0)
	v_pk_add_f32 v[32:33], v[32:33], v[34:35]
	ds_bpermute_b32 v35, v50, v33
	ds_bpermute_b32 v34, v50, v32
	s_waitcnt lgkmcnt(0)
	v_pk_add_f32 v[32:33], v[32:33], v[34:35]
	ds_bpermute_b32 v35, v48, v33
	ds_bpermute_b32 v34, v48, v32
	s_waitcnt lgkmcnt(0)
	v_pk_add_f32 v[32:33], v[32:33], v[34:35]
	ds_bpermute_b32 v35, v51, v33
	ds_bpermute_b32 v34, v51, v32
	s_waitcnt lgkmcnt(0)
	v_pk_add_f32 v[32:33], v[32:33], v[34:35]
	s_nop 0
	v_pk_fma_f32 v[32:33], v[32:33], s[4:5], v[22:23] op_sel_hi:[1,0,0]
	s_waitcnt vmcnt(4)
; __device__ __forceinline__ uint32_t pk2(float lo, float hi) { typedef float f2 __attribute__((ext_vector_type(2))); const f2 v = {lo, hi}; return __builtin_bit_cast(uint32_t, __builtin_convertvector(v, bf16x2_t)); }
; __device__ __forceinline__ float bflo(uint32_t u) { return __uint_as_float(u << 16); }
; __device__ __forceinline__ float bfhi(uint32_t u) { return __uint_as_float(u & 0xffff0000u); }
; __device__ __forceinline__ float siluf(float x) { return x * __builtin_amdgcn_rcpf(1.f + __expf(-x)); }
; __device__ __forceinline__ void dn3_item(const Params& p, int l, int item, unsigned char* lds) {
;     ...
;         const float rs = rsqrtf(ss * (1.f / 64.f) + EPS);
;         const size_t rowoff = (size_t)(t0 + 4 * ty + rr) * PBW + PB_DN + hd * 64 + 4 * tx;
;         const u32x2 z = *(const u32x2*)(PB + rowoff + 1536);
;         const float o0 = acc[rr][0] * rs * gn.x * siluf(bflo(z.x)), o1 = acc[rr][1] * rs * gn.y * siluf(bfhi(z.x));
;         const float o2 = acc[rr][2] * rs * gn.z * siluf(bflo(z.y)), o3 = acc[rr][3] * rs * gn.w * siluf(bfhi(z.y));
;         u32x2 w = {pk2(o0, o1), pk2(o2, o3)};
;         *(u32x2*)(PB + rowoff) = w;
;     }
	v_lshlrev_b32_e32 v34, 16, v26
	v_mul_f32_e32 v0, 0x4b800000, v33
	v_cmp_gt_f32_e32 vcc, s0, v33
	v_and_b32_e32 v35, 0xffff0000, v26
	v_lshlrev_b32_e32 v26, 16, v27
	v_and_b32_e32 v27, 0xffff0000, v27
	v_cndmask_b32_e32 v0, v33, v0, vcc
	v_mul_f32_e32 v33, 0xbfb8aa3b, v34
	v_mul_f32_e32 v44, 0xbfb8aa3b, v35
	v_mul_f32_e32 v45, 0xbfb8aa3b, v26
	v_mul_f32_e32 v46, 0xbfb8aa3b, v27
	v_exp_f32_e32 v33, v33
	v_exp_f32_e32 v44, v44
	v_exp_f32_e32 v45, v45
	v_exp_f32_e32 v46, v46
	v_rsq_f32_e32 v0, v0
	v_add_f32_e32 v33, 1.0, v33
	v_add_f32_e32 v47, 1.0, v44
	v_add_f32_e32 v52, 1.0, v45
	v_add_f32_e32 v53, 1.0, v46
	v_rcp_f32_e32 v44, v33
	v_rcp_f32_e32 v45, v47
	v_rcp_f32_e32 v46, v52
	v_rcp_f32_e32 v47, v53
	v_mul_f32_e32 v33, 0x45800000, v0
	v_cndmask_b32_e32 v0, v0, v33, vcc
	v_pk_mul_f32 v[14:15], v[14:15], v[0:1] op_sel_hi:[1,0]
	v_pk_mul_f32 v[16:17], v[16:17], v[0:1] op_sel_hi:[1,0]
	v_mul_f32_e32 v0, 0x4b800000, v32
	v_cmp_gt_f32_e32 vcc, s0, v32
	v_pk_mul_f32 v[34:35], v[44:45], v[34:35]
	v_pk_mul_f32 v[26:27], v[46:47], v[26:27]
	s_waitcnt vmcnt(3)
	v_pk_mul_f32 v[14:15], v[18:19], v[14:15]
	v_pk_mul_f32 v[16:17], v[20:21], v[16:17]
	v_cndmask_b32_e32 v0, v32, v0, vcc
	v_pk_mul_f32 v[14:15], v[34:35], v[14:15]
	v_pk_mul_f32 v[16:17], v[26:27], v[16:17]
	v_rsq_f32_e32 v0, v0
	v_cvt_pk_bf16_f32 v14, v14, v15
	v_cvt_pk_bf16_f32 v15, v16, v17
	global_store_dwordx2 v[24:25], v[14:15], off
	s_waitcnt vmcnt(3)
	v_lshlrev_b32_e32 v14, 16, v42
	v_mul_f32_e32 v15, 0xbfb8aa3b, v14
	v_exp_f32_e32 v16, v15
	v_mul_f32_e32 v15, 0x45800000, v0
	v_cndmask_b32_e32 v0, v0, v15, vcc
	v_and_b32_e32 v15, 0xffff0000, v42
	v_mul_f32_e32 v17, 0xbfb8aa3b, v15
	v_exp_f32_e32 v17, v17
	v_lshlrev_b32_e32 v24, 16, v43
	v_and_b32_e32 v25, 0xffff0000, v43
	v_add_f32_e32 v16, 1.0, v16
	v_add_f32_e32 v17, 1.0, v17
	v_mul_f32_e32 v26, 0xbfb8aa3b, v24
	v_mul_f32_e32 v27, 0xbfb8aa3b, v25
	v_rcp_f32_e32 v16, v16
	v_rcp_f32_e32 v17, v17
	v_exp_f32_e32 v26, v26
	v_exp_f32_e32 v27, v27
	v_pk_mul_f32 v[10:11], v[10:11], v[0:1] op_sel_hi:[1,0]
	v_pk_mul_f32 v[14:15], v[16:17], v[14:15]
	v_add_f32_e32 v16, 1.0, v26
	v_add_f32_e32 v17, 1.0, v27
	v_rcp_f32_e32 v16, v16
	v_rcp_f32_e32 v17, v17
	v_pk_mul_f32 v[10:11], v[18:19], v[10:11]
	v_pk_mul_f32 v[12:13], v[12:13], v[0:1] op_sel_hi:[1,0]
	v_pk_mul_f32 v[10:11], v[14:15], v[10:11]
	v_pk_mul_f32 v[12:13], v[20:21], v[12:13]
	v_pk_mul_f32 v[14:15], v[16:17], v[24:25]
	v_cvt_pk_bf16_f32 v10, v10, v11
	v_pk_mul_f32 v[12:13], v[14:15], v[12:13]
	v_pk_mul_f32 v[24:25], v[2:3], v[2:3]
	v_cvt_pk_bf16_f32 v11, v12, v13
	v_pk_mul_f32 v[12:13], v[6:7], v[6:7]
	v_pk_mul_f32 v[14:15], v[8:9], v[8:9]
	v_pk_mul_f32 v[26:27], v[4:5], v[4:5]
	v_mov_b32_e32 v32, v24
	v_mov_b32_e32 v33, v12
	v_mov_b32_e32 v12, v25
	v_pk_add_f32 v[12:13], v[32:33], v[12:13]
	v_mov_b32_e32 v24, v26
	v_mov_b32_e32 v25, v14
	v_pk_add_f32 v[12:13], v[24:25], v[12:13]
	v_mov_b32_e32 v14, v27
	v_pk_add_f32 v[12:13], v[14:15], v[12:13]
	ds_bpermute_b32 v15, v49, v13
	ds_bpermute_b32 v14, v49, v12
	s_waitcnt vmcnt(2)
	v_lshlrev_b32_e32 v16, 16, v38
	v_mul_f32_e32 v0, 0xbfb8aa3b, v16
	v_exp_f32_e32 v0, v0
	v_and_b32_e32 v17, 0xffff0000, v38
	s_waitcnt lgkmcnt(0)
	v_pk_add_f32 v[12:13], v[12:13], v[14:15]
	ds_bpermute_b32 v15, v50, v13
	ds_bpermute_b32 v14, v50, v12
	v_add_f32_e32 v0, 1.0, v0
	v_rcp_f32_e32 v24, v0
	v_mul_f32_e32 v0, 0xbfb8aa3b, v17
	v_exp_f32_e32 v0, v0
	s_waitcnt lgkmcnt(0)
	v_pk_add_f32 v[12:13], v[12:13], v[14:15]
	ds_bpermute_b32 v15, v48, v13
	ds_bpermute_b32 v14, v48, v12
	v_add_f32_e32 v0, 1.0, v0
	v_lshlrev_b32_e32 v26, 16, v39
	v_rcp_f32_e32 v25, v0
	v_and_b32_e32 v27, 0xffff0000, v39
	s_waitcnt lgkmcnt(0)
	v_pk_add_f32 v[12:13], v[12:13], v[14:15]
	v_mul_f32_e32 v0, 0xbfb8aa3b, v26
	ds_bpermute_b32 v15, v51, v13
	ds_bpermute_b32 v14, v51, v12
	v_exp_f32_e32 v0, v0
	v_mul_f32_e32 v32, 0xbfb8aa3b, v27
	v_exp_f32_e32 v33, v32
	global_store_dwordx2 v[28:29], v[10:11], off
	v_add_f32_e32 v0, 1.0, v0
	s_waitcnt lgkmcnt(0)
	v_pk_add_f32 v[12:13], v[12:13], v[14:15]
	v_rcp_f32_e32 v32, v0
	v_add_f32_e32 v0, 1.0, v33
	v_pk_fma_f32 v[12:13], v[12:13], s[4:5], v[22:23] op_sel_hi:[1,0,0]
	v_rcp_f32_e32 v33, v0
	v_mul_f32_e32 v0, 0x4b800000, v13
	v_cmp_gt_f32_e32 vcc, s0, v13
	v_pk_mul_f32 v[10:11], v[24:25], v[16:17]
	v_pk_mul_f32 v[14:15], v[32:33], v[26:27]
	v_cndmask_b32_e32 v0, v13, v0, vcc
	v_rsq_f32_e32 v0, v0
	s_nop 0
	v_mul_f32_e32 v13, 0x45800000, v0
	v_cndmask_b32_e32 v0, v0, v13, vcc
	v_pk_mul_f32 v[6:7], v[6:7], v[0:1] op_sel_hi:[1,0]
	v_pk_mul_f32 v[8:9], v[8:9], v[0:1] op_sel_hi:[1,0]
	v_mul_f32_e32 v0, 0x4b800000, v12
	v_cmp_gt_f32_e32 vcc, s0, v12
	v_pk_mul_f32 v[6:7], v[18:19], v[6:7]
	v_pk_mul_f32 v[8:9], v[20:21], v[8:9]
	v_cndmask_b32_e32 v0, v12, v0, vcc
	v_pk_mul_f32 v[6:7], v[10:11], v[6:7]
	v_pk_mul_f32 v[8:9], v[14:15], v[8:9]
	v_rsq_f32_e32 v0, v0
	v_cvt_pk_bf16_f32 v6, v6, v7
	v_cvt_pk_bf16_f32 v7, v8, v9
	global_store_dwordx2 v[36:37], v[6:7], off
	s_waitcnt vmcnt(3)
	v_lshlrev_b32_e32 v6, 16, v40
	v_mul_f32_e32 v7, 0xbfb8aa3b, v6
	v_exp_f32_e32 v8, v7
	v_mul_f32_e32 v7, 0x45800000, v0
	v_cndmask_b32_e32 v0, v0, v7, vcc
	v_and_b32_e32 v7, 0xffff0000, v40
	v_mul_f32_e32 v9, 0xbfb8aa3b, v7
	v_exp_f32_e32 v9, v9
	v_lshlrev_b32_e32 v10, 16, v41
	v_and_b32_e32 v11, 0xffff0000, v41
	v_add_f32_e32 v8, 1.0, v8
	v_add_f32_e32 v9, 1.0, v9
	v_mul_f32_e32 v12, 0xbfb8aa3b, v10
	v_mul_f32_e32 v13, 0xbfb8aa3b, v11
	v_rcp_f32_e32 v8, v8
	v_rcp_f32_e32 v9, v9
	v_exp_f32_e32 v12, v12
	v_exp_f32_e32 v13, v13
	v_pk_mul_f32 v[2:3], v[2:3], v[0:1] op_sel_hi:[1,0]
	v_pk_mul_f32 v[6:7], v[8:9], v[6:7]
	v_add_f32_e32 v8, 1.0, v12
	v_add_f32_e32 v9, 1.0, v13
	v_rcp_f32_e32 v8, v8
	v_rcp_f32_e32 v9, v9
	v_pk_mul_f32 v[2:3], v[18:19], v[2:3]
	v_pk_mul_f32 v[4:5], v[4:5], v[0:1] op_sel_hi:[1,0]
	v_pk_mul_f32 v[2:3], v[6:7], v[2:3]
	v_pk_mul_f32 v[4:5], v[20:21], v[4:5]
	v_pk_mul_f32 v[6:7], v[8:9], v[10:11]
	v_cvt_pk_bf16_f32 v2, v2, v3
	v_pk_mul_f32 v[4:5], v[6:7], v[4:5]
	s_nop 0
	v_cvt_pk_bf16_f32 v3, v4, v5
	global_store_dwordx2 v[30:31], v[2:3], off
	s_branch .LBB0_136

; #define ZERO44(a) { _Pragma("unroll") for (int _i = 0; _i < 4; ++_i) { _Pragma("unroll") for (int _j = 0; _j < 4; ++_j) a[_i][_j] = 0.f; } }
; __device__ __forceinline__ void dn1_item(const Params& p, int l, int item, unsigned char* lds) {
;     ...
;     const float gci = sgc[i], beti = sbeta[i], gcl = sgc[63];
;     const float gl = __expf(gcl);
;     {
;         float a1[4][4], a2[4][4]; ZERO44(a1); ZERO44(a2);
;         mm64(B0, B0, a1, ty, tx);
;         mm64(B1, B0, a2, ty, tx);
.LBB0_587:
	s_or_b64 exec, exec, s[0:1]
	v_lshl_add_u32 v0, v108, 2, 0
	v_add_u32_e32 v2, 0x11000, v0
	v_readlane_b32 s0, v253, 48
	s_waitcnt lgkmcnt(0)
	s_barrier
	v_add_u32_e32 v0, 0x11100, v0
	v_mov_b32_e32 v3, s0
	ds_read_b32 v109, v2
	ds_read_b32 v92, v0
	ds_read_b32 v106, v3
	v_ashrrev_i32_e32 v104, 4, v107
	v_and_b32_e32 v111, 15, v107
	v_and_b32_e32 v0, -16, v107
	v_mov_b32_e32 v2, 0
	v_lshlrev_b32_e32 v105, 2, v104
	v_add_u32_e32 v51, 0, v0
	v_lshlrev_b32_e32 v50, 2, v111
	v_lshl_add_u32 v76, v111, 4, 0
	s_mov_b32 s0, 0
	v_mov_b32_e32 v3, v2
	v_mov_b32_e32 v16, v2
	v_mov_b32_e32 v17, v2
	v_mov_b32_e32 v14, v2
	v_mov_b32_e32 v15, v2
	v_mov_b32_e32 v12, v2
	v_mov_b32_e32 v13, v2
	v_mov_b32_e32 v10, v2
	v_mov_b32_e32 v11, v2
	v_mov_b32_e32 v8, v2
	v_mov_b32_e32 v9, v2
	v_mov_b32_e32 v6, v2
	v_mov_b32_e32 v7, v2
	v_mov_b32_e32 v4, v2
	v_mov_b32_e32 v5, v2
	v_add_u32_e32 v220, s0, v51
	v_add_u32_e32 v221, s0, v76
	ds_read_b128 v[204:207], v220
	ds_read_b128 v[208:211], v221
.LBB0_588:
	ds_read_b128 v[212:215], v220 offset:272
	ds_read_b128 v[216:219], v221 offset:272
	s_waitcnt lgkmcnt(2)
	v_pk_fma_f32 v[16:17], v[204:205], v[208:209], v[16:17] op_sel_hi:[0,1,1]
	v_pk_fma_f32 v[14:15], v[204:205], v[210:211], v[14:15] op_sel_hi:[0,1,1]
	v_pk_fma_f32 v[12:13], v[204:205], v[208:209], v[12:13] op_sel:[1,0,0]
	v_pk_fma_f32 v[10:11], v[204:205], v[210:211], v[10:11] op_sel:[1,0,0]
	v_pk_fma_f32 v[8:9], v[206:207], v[208:209], v[8:9] op_sel_hi:[0,1,1]
	v_pk_fma_f32 v[6:7], v[206:207], v[210:211], v[6:7] op_sel_hi:[0,1,1]
	v_pk_fma_f32 v[4:5], v[206:207], v[208:209], v[4:5] op_sel:[1,0,0]
	v_pk_fma_f32 v[2:3], v[206:207], v[210:211], v[2:3] op_sel:[1,0,0]
	ds_read_b128 v[204:207], v220 offset:544
	ds_read_b128 v[208:211], v221 offset:544
	s_waitcnt lgkmcnt(2)
	v_pk_fma_f32 v[16:17], v[212:213], v[216:217], v[16:17] op_sel_hi:[0,1,1]
	v_pk_fma_f32 v[14:15], v[212:213], v[218:219], v[14:15] op_sel_hi:[0,1,1]
	v_pk_fma_f32 v[12:13], v[212:213], v[216:217], v[12:13] op_sel:[1,0,0]
	v_pk_fma_f32 v[10:11], v[212:213], v[218:219], v[10:11] op_sel:[1,0,0]
	v_pk_fma_f32 v[8:9], v[214:215], v[216:217], v[8:9] op_sel_hi:[0,1,1]
	v_pk_fma_f32 v[6:7], v[214:215], v[218:219], v[6:7] op_sel_hi:[0,1,1]
	v_pk_fma_f32 v[4:5], v[214:215], v[216:217], v[4:5] op_sel:[1,0,0]
	v_pk_fma_f32 v[2:3], v[214:215], v[218:219], v[2:3] op_sel:[1,0,0]
	ds_read_b128 v[212:215], v220 offset:816
	ds_read_b128 v[216:219], v221 offset:816
	s_waitcnt lgkmcnt(2)
	v_pk_fma_f32 v[16:17], v[204:205], v[208:209], v[16:17] op_sel_hi:[0,1,1]
	v_pk_fma_f32 v[14:15], v[204:205], v[210:211], v[14:15] op_sel_hi:[0,1,1]
	v_pk_fma_f32 v[12:13], v[204:205], v[208:209], v[12:13] op_sel:[1,0,0]
	v_pk_fma_f32 v[10:11], v[204:205], v[210:211], v[10:11] op_sel:[1,0,0]
	v_pk_fma_f32 v[8:9], v[206:207], v[208:209], v[8:9] op_sel_hi:[0,1,1]
	v_pk_fma_f32 v[6:7], v[206:207], v[210:211], v[6:7] op_sel_hi:[0,1,1]
	v_pk_fma_f32 v[4:5], v[206:207], v[208:209], v[4:5] op_sel:[1,0,0]
	v_pk_fma_f32 v[2:3], v[206:207], v[210:211], v[2:3] op_sel:[1,0,0]
	ds_read_b128 v[204:207], v220 offset:1088
	ds_read_b128 v[208:211], v221 offset:1088
	s_waitcnt lgkmcnt(2)
	v_pk_fma_f32 v[16:17], v[212:213], v[216:217], v[16:17] op_sel_hi:[0,1,1]
	v_pk_fma_f32 v[14:15], v[212:213], v[218:219], v[14:15] op_sel_hi:[0,1,1]
	v_pk_fma_f32 v[12:13], v[212:213], v[216:217], v[12:13] op_sel:[1,0,0]
	v_pk_fma_f32 v[10:11], v[212:213], v[218:219], v[10:11] op_sel:[1,0,0]
	v_pk_fma_f32 v[8:9], v[214:215], v[216:217], v[8:9] op_sel_hi:[0,1,1]
	v_pk_fma_f32 v[6:7], v[214:215], v[218:219], v[6:7] op_sel_hi:[0,1,1]
	v_pk_fma_f32 v[4:5], v[214:215], v[216:217], v[4:5] op_sel:[1,0,0]
	v_pk_fma_f32 v[2:3], v[214:215], v[218:219], v[2:3] op_sel:[1,0,0]
	ds_read_b128 v[212:215], v220 offset:1360
	ds_read_b128 v[216:219], v221 offset:1360
	s_waitcnt lgkmcnt(2)
	v_pk_fma_f32 v[16:17], v[204:205], v[208:209], v[16:17] op_sel_hi:[0,1,1]
	v_pk_fma_f32 v[14:15], v[204:205], v[210:211], v[14:15] op_sel_hi:[0,1,1]
	v_pk_fma_f32 v[12:13], v[204:205], v[208:209], v[12:13] op_sel:[1,0,0]
	v_pk_fma_f32 v[10:11], v[204:205], v[210:211], v[10:11] op_sel:[1,0,0]
	v_pk_fma_f32 v[8:9], v[206:207], v[208:209], v[8:9] op_sel_hi:[0,1,1]
	v_pk_fma_f32 v[6:7], v[206:207], v[210:211], v[6:7] op_sel_hi:[0,1,1]
	v_pk_fma_f32 v[4:5], v[206:207], v[208:209], v[4:5] op_sel:[1,0,0]
	v_pk_fma_f32 v[2:3], v[206:207], v[210:211], v[2:3] op_sel:[1,0,0]
	ds_read_b128 v[204:207], v220 offset:1632
	ds_read_b128 v[208:211], v221 offset:1632
	s_waitcnt lgkmcnt(2)
	v_pk_fma_f32 v[16:17], v[212:213], v[216:217], v[16:17] op_sel_hi:[0,1,1]
	v_pk_fma_f32 v[14:15], v[212:213], v[218:219], v[14:15] op_sel_hi:[0,1,1]
	v_pk_fma_f32 v[12:13], v[212:213], v[216:217], v[12:13] op_sel:[1,0,0]
	v_pk_fma_f32 v[10:11], v[212:213], v[218:219], v[10:11] op_sel:[1,0,0]
	v_pk_fma_f32 v[8:9], v[214:215], v[216:217], v[8:9] op_sel_hi:[0,1,1]
	v_pk_fma_f32 v[6:7], v[214:215], v[218:219], v[6:7] op_sel_hi:[0,1,1]
	v_pk_fma_f32 v[4:5], v[214:215], v[216:217], v[4:5] op_sel:[1,0,0]
	v_pk_fma_f32 v[2:3], v[214:215], v[218:219], v[2:3] op_sel:[1,0,0]
	ds_read_b128 v[212:215], v220 offset:1904
	ds_read_b128 v[216:219], v221 offset:1904
	s_waitcnt lgkmcnt(2)
	v_pk_fma_f32 v[16:17], v[204:205], v[208:209], v[16:17] op_sel_hi:[0,1,1]
	v_pk_fma_f32 v[14:15], v[204:205], v[210:211], v[14:15] op_sel_hi:[0,1,1]
	v_pk_fma_f32 v[12:13], v[204:205], v[208:209], v[12:13] op_sel:[1,0,0]
	v_pk_fma_f32 v[10:11], v[204:205], v[210:211], v[10:11] op_sel:[1,0,0]
	v_pk_fma_f32 v[8:9], v[206:207], v[208:209], v[8:9] op_sel_hi:[0,1,1]
	v_pk_fma_f32 v[6:7], v[206:207], v[210:211], v[6:7] op_sel_hi:[0,1,1]
	v_pk_fma_f32 v[4:5], v[206:207], v[208:209], v[4:5] op_sel:[1,0,0]
	v_pk_fma_f32 v[2:3], v[206:207], v[210:211], v[2:3] op_sel:[1,0,0]
	s_addk_i32 s0, 0x880
	v_add_u32_e32 v220, s0, v51
	v_add_u32_e32 v221, s0, v76
	ds_read_b128 v[204:207], v220
	ds_read_b128 v[208:211], v221
	s_waitcnt lgkmcnt(2)
	v_pk_fma_f32 v[16:17], v[212:213], v[216:217], v[16:17] op_sel_hi:[0,1,1]
	v_pk_fma_f32 v[14:15], v[212:213], v[218:219], v[14:15] op_sel_hi:[0,1,1]
	v_pk_fma_f32 v[12:13], v[212:213], v[216:217], v[12:13] op_sel:[1,0,0]
	v_pk_fma_f32 v[10:11], v[212:213], v[218:219], v[10:11] op_sel:[1,0,0]
	v_pk_fma_f32 v[8:9], v[214:215], v[216:217], v[8:9] op_sel_hi:[0,1,1]
	v_pk_fma_f32 v[6:7], v[214:215], v[218:219], v[6:7] op_sel_hi:[0,1,1]
	v_pk_fma_f32 v[4:5], v[214:215], v[216:217], v[4:5] op_sel:[1,0,0]
	v_pk_fma_f32 v[2:3], v[214:215], v[218:219], v[2:3] op_sel:[1,0,0]
	s_cmpk_lg_i32 s0, 0x4400
	s_cbranch_scc1 .LBB0_588
; #define ZERO44(a) { _Pragma("unroll") for (int _i = 0; _i < 4; ++_i) { _Pragma("unroll") for (int _j = 0; _j < 4; ++_j) a[_i][_j] = 0.f; } }
; __device__ __forceinline__ void dn1_item(const Params& p, int l, int item, unsigned char* lds) {
;     ...
;         float a1[4][4], a2[4][4]; ZERO44(a1); ZERO44(a2);
;         mm64(B0, B0, a1, ty, tx);
;         mm64(B1, B0, a2, ty, tx);
; #pragma unroll
;         for (int rr = 0; rr < 4; ++rr) {
;             const int ii = 4 * ty + rr; const float gi = sgc[ii], bi = sbeta[ii];
; #pragma unroll
;             for (int cc = 0; cc < 4; ++cc) {
;                 const int jj = 4 * tx + cc; const float gj = sgc[jj];
;                 const float dec = (ii >= jj) ? __expf(gi - gj) : 0.f;
	s_waitcnt lgkmcnt(0)
	v_lshlrev_b32_e32 v77, 4, v104
	v_readlane_b32 s0, v253, 47
	v_mov_b32_e32 v18, 0
	v_mov_b32_e32 v19, v18
	v_add_u32_e32 v93, s0, v77
	s_mov_b32 s0, 0
	v_mov_b32_e32 v102, v18
	v_mov_b32_e32 v103, v18
	v_mov_b32_e32 v100, v18
	v_mov_b32_e32 v101, v18
	v_mov_b32_e32 v98, v18
	v_mov_b32_e32 v99, v18
	v_mov_b32_e32 v96, v18
	v_mov_b32_e32 v97, v18
	v_mov_b32_e32 v94, v18
	v_mov_b32_e32 v95, v18
	v_mov_b32_e32 v52, v18
	v_mov_b32_e32 v53, v18
	v_mov_b32_e32 v20, v18
	v_mov_b32_e32 v21, v18
	v_add_u32_e32 v220, s0, v93
	v_add_u32_e32 v221, s0, v76
	ds_read_b128 v[204:207], v220
	ds_read_b128 v[208:211], v221
.LBB0_590:
	ds_read_b128 v[212:215], v220 offset:272
	ds_read_b128 v[216:219], v221 offset:272
	s_waitcnt lgkmcnt(2)
	v_pk_fma_f32 v[102:103], v[204:205], v[208:209], v[102:103] op_sel_hi:[0,1,1]
	v_pk_fma_f32 v[100:101], v[204:205], v[210:211], v[100:101] op_sel_hi:[0,1,1]
	v_pk_fma_f32 v[98:99], v[204:205], v[208:209], v[98:99] op_sel:[1,0,0]
	v_pk_fma_f32 v[96:97], v[204:205], v[210:211], v[96:97] op_sel:[1,0,0]
	v_pk_fma_f32 v[94:95], v[206:207], v[208:209], v[94:95] op_sel_hi:[0,1,1]
	v_pk_fma_f32 v[52:53], v[206:207], v[210:211], v[52:53] op_sel_hi:[0,1,1]
	v_pk_fma_f32 v[20:21], v[206:207], v[208:209], v[20:21] op_sel:[1,0,0]
	v_pk_fma_f32 v[18:19], v[206:207], v[210:211], v[18:19] op_sel:[1,0,0]
	ds_read_b128 v[204:207], v220 offset:544
	ds_read_b128 v[208:211], v221 offset:544
	s_waitcnt lgkmcnt(2)
	v_pk_fma_f32 v[102:103], v[212:213], v[216:217], v[102:103] op_sel_hi:[0,1,1]
	v_pk_fma_f32 v[100:101], v[212:213], v[218:219], v[100:101] op_sel_hi:[0,1,1]
	v_pk_fma_f32 v[98:99], v[212:213], v[216:217], v[98:99] op_sel:[1,0,0]
	v_pk_fma_f32 v[96:97], v[212:213], v[218:219], v[96:97] op_sel:[1,0,0]
	v_pk_fma_f32 v[94:95], v[214:215], v[216:217], v[94:95] op_sel_hi:[0,1,1]
	v_pk_fma_f32 v[52:53], v[214:215], v[218:219], v[52:53] op_sel_hi:[0,1,1]
	v_pk_fma_f32 v[20:21], v[214:215], v[216:217], v[20:21] op_sel:[1,0,0]
	v_pk_fma_f32 v[18:19], v[214:215], v[218:219], v[18:19] op_sel:[1,0,0]
	ds_read_b128 v[212:215], v220 offset:816
	ds_read_b128 v[216:219], v221 offset:816
	s_waitcnt lgkmcnt(2)
	v_pk_fma_f32 v[102:103], v[204:205], v[208:209], v[102:103] op_sel_hi:[0,1,1]
	v_pk_fma_f32 v[100:101], v[204:205], v[210:211], v[100:101] op_sel_hi:[0,1,1]
	v_pk_fma_f32 v[98:99], v[204:205], v[208:209], v[98:99] op_sel:[1,0,0]
	v_pk_fma_f32 v[96:97], v[204:205], v[210:211], v[96:97] op_sel:[1,0,0]
	v_pk_fma_f32 v[94:95], v[206:207], v[208:209], v[94:95] op_sel_hi:[0,1,1]
	v_pk_fma_f32 v[52:53], v[206:207], v[210:211], v[52:53] op_sel_hi:[0,1,1]
	v_pk_fma_f32 v[20:21], v[206:207], v[208:209], v[20:21] op_sel:[1,0,0]
	v_pk_fma_f32 v[18:19], v[206:207], v[210:211], v[18:19] op_sel:[1,0,0]
	ds_read_b128 v[204:207], v220 offset:1088
	ds_read_b128 v[208:211], v221 offset:1088
	s_waitcnt lgkmcnt(2)
	v_pk_fma_f32 v[102:103], v[212:213], v[216:217], v[102:103] op_sel_hi:[0,1,1]
	v_pk_fma_f32 v[100:101], v[212:213], v[218:219], v[100:101] op_sel_hi:[0,1,1]
	v_pk_fma_f32 v[98:99], v[212:213], v[216:217], v[98:99] op_sel:[1,0,0]
	v_pk_fma_f32 v[96:97], v[212:213], v[218:219], v[96:97] op_sel:[1,0,0]
	v_pk_fma_f32 v[94:95], v[214:215], v[216:217], v[94:95] op_sel_hi:[0,1,1]
	v_pk_fma_f32 v[52:53], v[214:215], v[218:219], v[52:53] op_sel_hi:[0,1,1]
	v_pk_fma_f32 v[20:21], v[214:215], v[216:217], v[20:21] op_sel:[1,0,0]
	v_pk_fma_f32 v[18:19], v[214:215], v[218:219], v[18:19] op_sel:[1,0,0]
	ds_read_b128 v[212:215], v220 offset:1360
	ds_read_b128 v[216:219], v221 offset:1360
	s_waitcnt lgkmcnt(2)
	v_pk_fma_f32 v[102:103], v[204:205], v[208:209], v[102:103] op_sel_hi:[0,1,1]
	v_pk_fma_f32 v[100:101], v[204:205], v[210:211], v[100:101] op_sel_hi:[0,1,1]
	v_pk_fma_f32 v[98:99], v[204:205], v[208:209], v[98:99] op_sel:[1,0,0]
	v_pk_fma_f32 v[96:97], v[204:205], v[210:211], v[96:97] op_sel:[1,0,0]
	v_pk_fma_f32 v[94:95], v[206:207], v[208:209], v[94:95] op_sel_hi:[0,1,1]
	v_pk_fma_f32 v[52:53], v[206:207], v[210:211], v[52:53] op_sel_hi:[0,1,1]
	v_pk_fma_f32 v[20:21], v[206:207], v[208:209], v[20:21] op_sel:[1,0,0]
	v_pk_fma_f32 v[18:19], v[206:207], v[210:211], v[18:19] op_sel:[1,0,0]
	ds_read_b128 v[204:207], v220 offset:1632
	ds_read_b128 v[208:211], v221 offset:1632
	s_waitcnt lgkmcnt(2)
	v_pk_fma_f32 v[102:103], v[212:213], v[216:217], v[102:103] op_sel_hi:[0,1,1]
	v_pk_fma_f32 v[100:101], v[212:213], v[218:219], v[100:101] op_sel_hi:[0,1,1]
	v_pk_fma_f32 v[98:99], v[212:213], v[216:217], v[98:99] op_sel:[1,0,0]
	v_pk_fma_f32 v[96:97], v[212:213], v[218:219], v[96:97] op_sel:[1,0,0]
	v_pk_fma_f32 v[94:95], v[214:215], v[216:217], v[94:95] op_sel_hi:[0,1,1]
	v_pk_fma_f32 v[52:53], v[214:215], v[218:219], v[52:53] op_sel_hi:[0,1,1]
	v_pk_fma_f32 v[20:21], v[214:215], v[216:217], v[20:21] op_sel:[1,0,0]
	v_pk_fma_f32 v[18:19], v[214:215], v[218:219], v[18:19] op_sel:[1,0,0]
	ds_read_b128 v[212:215], v220 offset:1904
	ds_read_b128 v[216:219], v221 offset:1904
	s_waitcnt lgkmcnt(2)
	v_pk_fma_f32 v[102:103], v[204:205], v[208:209], v[102:103] op_sel_hi:[0,1,1]
	v_pk_fma_f32 v[100:101], v[204:205], v[210:211], v[100:101] op_sel_hi:[0,1,1]
	v_pk_fma_f32 v[98:99], v[204:205], v[208:209], v[98:99] op_sel:[1,0,0]
	v_pk_fma_f32 v[96:97], v[204:205], v[210:211], v[96:97] op_sel:[1,0,0]
	v_pk_fma_f32 v[94:95], v[206:207], v[208:209], v[94:95] op_sel_hi:[0,1,1]
	v_pk_fma_f32 v[52:53], v[206:207], v[210:211], v[52:53] op_sel_hi:[0,1,1]
	v_pk_fma_f32 v[20:21], v[206:207], v[208:209], v[20:21] op_sel:[1,0,0]
	v_pk_fma_f32 v[18:19], v[206:207], v[210:211], v[18:19] op_sel:[1,0,0]
	s_addk_i32 s0, 0x880
	v_add_u32_e32 v220, s0, v93
	v_add_u32_e32 v221, s0, v76
	ds_read_b128 v[204:207], v220
	ds_read_b128 v[208:211], v221
	s_waitcnt lgkmcnt(2)
	v_pk_fma_f32 v[102:103], v[212:213], v[216:217], v[102:103] op_sel_hi:[0,1,1]
	v_pk_fma_f32 v[100:101], v[212:213], v[218:219], v[100:101] op_sel_hi:[0,1,1]
	v_pk_fma_f32 v[98:99], v[212:213], v[216:217], v[98:99] op_sel:[1,0,0]
	v_pk_fma_f32 v[96:97], v[212:213], v[218:219], v[96:97] op_sel:[1,0,0]
	v_pk_fma_f32 v[94:95], v[214:215], v[216:217], v[94:95] op_sel_hi:[0,1,1]
	v_pk_fma_f32 v[52:53], v[214:215], v[218:219], v[52:53] op_sel_hi:[0,1,1]
	v_pk_fma_f32 v[20:21], v[214:215], v[216:217], v[20:21] op_sel:[1,0,0]
	v_pk_fma_f32 v[18:19], v[214:215], v[218:219], v[18:19] op_sel:[1,0,0]
	s_cmpk_lg_i32 s0, 0x4400
	s_cbranch_scc1 .LBB0_590
	s_waitcnt lgkmcnt(0)
	v_lshl_add_u32 v0, v105, 2, 0
	v_add_u32_e32 v113, 0x11000, v0
	v_add_u32_e32 v0, 0x11100, v0
	ds_read_b32 v118, v113
	ds_read_b32 v117, v0
	v_cmp_lt_i32_e64 s[40:41], v105, v50
	v_cmp_ge_i32_e32 vcc, v105, v50
	v_mov_b32_e32 v115, 0
	v_lshl_add_u32 v113, v50, 2, 0
	v_mov_b32_e32 v114, 0
	s_and_saveexec_b64 s[0:1], vcc
	s_cbranch_execz .LBB0_593
	v_add_u32_e32 v0, 0x11000, v113
	ds_read_b32 v0, v0
	s_waitcnt lgkmcnt(0)
	v_sub_f32_e32 v0, v118, v0
	v_mul_f32_e32 v0, 0x3fb8aa3b, v0
	v_exp_f32_e32 v114, v0

; #define ZERO44(a) { _Pragma("unroll") for (int _i = 0; _i < 4; ++_i) { _Pragma("unroll") for (int _j = 0; _j < 4; ++_j) a[_i][_j] = 0.f; } }
; __device__ __forceinline__ void dn1_item(const Params& p, int l, int item, unsigned char* lds) {
;     ...
; #pragma unroll 1
;             for (int bj = 0; bj < bi; ++bj) {
;                 float y = 0.f;
; #pragma unroll
;                 for (int m = 0; m < 16; ++m) y += B0[(16 * bi + m) * DLD + 16 * bi + br] * Xs[bj * 256 + m * 16 + bc];
;                 B0[(16 * bj + bc) * DLD + 16 * bi + br] = -y;
;             }
;             __syncthreads();
;         }
;     }
;     __syncthreads();
;     float wacc[4][4], uacc[4][4]; ZERO44(wacc); ZERO44(uacc);
;     mm64(B0, B1, wacc, ty, tx);
.LBB0_631:
	v_add_u32_e32 v14, 0, v8
	v_add_u32_e32 v12, 0x11200, v14
	ds_read2_b32 v[10:11], v7 offset1:68
	ds_read_b32 v12, v12
	v_add_u32_e32 v13, 0x11340, v14
	v_add_u32_e32 v16, 0x400, v7
	s_add_i32 s1, s1, -1
	v_add_u32_e32 v8, 0x400, v8
	s_waitcnt lgkmcnt(0)
	v_fma_f32 v15, v10, v12, 0
	v_add_u32_e32 v10, 0x11240, v14
	ds_read_b32 v10, v10
	ds_read_b32 v13, v13
	v_add_u32_e32 v12, 0x11280, v14
	ds_read_b32 v12, v12
	s_cmp_lg_u32 s1, 0
	s_waitcnt lgkmcnt(2)
	v_fmac_f32_e32 v15, v11, v10
	ds_read2_b32 v[10:11], v7 offset0:136 offset1:204
	s_waitcnt lgkmcnt(0)
	v_fmac_f32_e32 v15, v10, v12
	v_add_u32_e32 v10, 0x112c0, v14
	ds_read_b32 v10, v10
	v_add_u32_e32 v12, 0x11300, v14
	ds_read_b32 v12, v12
	s_waitcnt lgkmcnt(1)
	v_fmac_f32_e32 v15, v11, v10
	ds_read2_b32 v[10:11], v16 offset0:16 offset1:84
	s_waitcnt lgkmcnt(0)
	v_pk_mul_f32 v[10:11], v[10:11], v[12:13]
	s_nop 0
	v_add_f32_e32 v10, v15, v10
	v_add_u32_e32 v12, 0x11380, v14
	v_add_u32_e32 v13, 0x113c0, v14
	v_add_f32_e32 v15, v10, v11
	ds_read2_b32 v[10:11], v16 offset0:152 offset1:220
	ds_read_b32 v12, v12
	ds_read_b32 v13, v13
	v_add_u32_e32 v16, 0x800, v7
	s_waitcnt lgkmcnt(0)
	v_pk_mul_f32 v[10:11], v[10:11], v[12:13]
	s_nop 0
	v_add_f32_e32 v10, v15, v10
	v_add_u32_e32 v12, 0x11400, v14
	v_add_u32_e32 v13, 0x11440, v14
	v_add_f32_e32 v15, v10, v11
	ds_read2_b32 v[10:11], v16 offset0:32 offset1:100
	ds_read_b32 v12, v12
	ds_read_b32 v13, v13
	s_waitcnt lgkmcnt(0)
	v_pk_mul_f32 v[10:11], v[10:11], v[12:13]
	s_nop 0
	v_add_f32_e32 v10, v15, v10
	v_add_u32_e32 v12, 0x11480, v14
	v_add_u32_e32 v13, 0x114c0, v14
	v_add_f32_e32 v15, v10, v11
	ds_read2_b32 v[10:11], v16 offset0:168 offset1:236
	ds_read_b32 v12, v12
	ds_read_b32 v13, v13
	v_add_u32_e32 v16, 0xc00, v7
	s_waitcnt lgkmcnt(0)
	v_pk_mul_f32 v[10:11], v[10:11], v[12:13]
	s_nop 0
	v_add_f32_e32 v10, v15, v10
	v_add_u32_e32 v12, 0x11500, v14
	v_add_u32_e32 v13, 0x11540, v14
	v_add_f32_e32 v15, v10, v11
	ds_read2_b32 v[10:11], v16 offset0:48 offset1:116
	ds_read_b32 v12, v12
	ds_read_b32 v13, v13
	s_waitcnt lgkmcnt(0)
	v_pk_mul_f32 v[10:11], v[10:11], v[12:13]
	s_nop 0
	v_add_f32_e32 v10, v15, v10
	v_add_u32_e32 v12, 0x11580, v14
	v_add_u32_e32 v13, 0x115c0, v14
	v_add_f32_e32 v15, v10, v11
	ds_read2_b32 v[10:11], v16 offset0:184 offset1:252
	ds_read_b32 v12, v12
	ds_read_b32 v13, v13
	s_waitcnt lgkmcnt(0)
	v_pk_mul_f32 v[10:11], v[10:11], v[12:13]
	s_nop 0
	v_add_f32_e32 v10, v15, v10
	v_add_f32_e32 v10, v10, v11
	v_xor_b32_e32 v10, 0x80000000, v10
	v_add_u32_e32 v11, 0, v9
	v_add_u32_e32 v9, 0x1100, v9
	ds_write_b32 v11, v10
	s_cbranch_scc1 .LBB0_631
	s_add_i32 s0, s0, 1
	v_add_u32_e32 v4, 0x1100, v4
	s_cmp_eq_u32 s0, 4
	v_add_u32_e32 v6, 64, v6
	s_waitcnt lgkmcnt(0)
	s_barrier
	s_cbranch_scc0 .LBB0_626
	v_lshlrev_b32_e32 v94, 4, v111
	v_readlane_b32 s0, v253, 47
	v_mov_b32_e32 v4, 0
	v_mov_b32_e32 v5, v4
	v_add_u32_e32 v95, s0, v94
	s_mov_b32 s0, 0
	v_mov_b32_e32 v14, v4
	v_mov_b32_e32 v15, v4
	v_mov_b32_e32 v16, v4
	v_mov_b32_e32 v17, v4
	v_mov_b32_e32 v10, v4
	v_mov_b32_e32 v11, v4
	v_mov_b32_e32 v12, v4
	v_mov_b32_e32 v13, v4
	v_mov_b32_e32 v6, v4
	v_mov_b32_e32 v7, v4
	v_mov_b32_e32 v8, v4
	v_mov_b32_e32 v9, v4
	v_mov_b32_e32 v2, v4
	v_mov_b32_e32 v3, v4
	s_barrier
	v_add_u32_e32 v220, s0, v51
	v_add_u32_e32 v221, s0, v95
	ds_read_b128 v[204:207], v220
	ds_read_b128 v[208:211], v221
.LBB0_634:
	ds_read_b128 v[212:215], v220 offset:272
	ds_read_b128 v[216:219], v221 offset:272
	s_waitcnt lgkmcnt(2)
	v_pk_fma_f32 v[14:15], v[204:205], v[208:209], v[14:15] op_sel_hi:[0,1,1]
	v_pk_fma_f32 v[16:17], v[204:205], v[210:211], v[16:17] op_sel_hi:[0,1,1]
	v_pk_fma_f32 v[10:11], v[204:205], v[208:209], v[10:11] op_sel:[1,0,0]
	v_pk_fma_f32 v[12:13], v[204:205], v[210:211], v[12:13] op_sel:[1,0,0]
	v_pk_fma_f32 v[6:7], v[206:207], v[208:209], v[6:7] op_sel_hi:[0,1,1]
	v_pk_fma_f32 v[8:9], v[206:207], v[210:211], v[8:9] op_sel_hi:[0,1,1]
	v_pk_fma_f32 v[2:3], v[206:207], v[208:209], v[2:3] op_sel:[1,0,0]
	v_pk_fma_f32 v[4:5], v[206:207], v[210:211], v[4:5] op_sel:[1,0,0]
	ds_read_b128 v[204:207], v220 offset:544
	ds_read_b128 v[208:211], v221 offset:544
	s_waitcnt lgkmcnt(2)
	v_pk_fma_f32 v[14:15], v[212:213], v[216:217], v[14:15] op_sel_hi:[0,1,1]
	v_pk_fma_f32 v[16:17], v[212:213], v[218:219], v[16:17] op_sel_hi:[0,1,1]
	v_pk_fma_f32 v[10:11], v[212:213], v[216:217], v[10:11] op_sel:[1,0,0]
	v_pk_fma_f32 v[12:13], v[212:213], v[218:219], v[12:13] op_sel:[1,0,0]
	v_pk_fma_f32 v[6:7], v[214:215], v[216:217], v[6:7] op_sel_hi:[0,1,1]
	v_pk_fma_f32 v[8:9], v[214:215], v[218:219], v[8:9] op_sel_hi:[0,1,1]
	v_pk_fma_f32 v[2:3], v[214:215], v[216:217], v[2:3] op_sel:[1,0,0]
	v_pk_fma_f32 v[4:5], v[214:215], v[218:219], v[4:5] op_sel:[1,0,0]
	ds_read_b128 v[212:215], v220 offset:816
	ds_read_b128 v[216:219], v221 offset:816
	s_waitcnt lgkmcnt(2)
	v_pk_fma_f32 v[14:15], v[204:205], v[208:209], v[14:15] op_sel_hi:[0,1,1]
	v_pk_fma_f32 v[16:17], v[204:205], v[210:211], v[16:17] op_sel_hi:[0,1,1]
	v_pk_fma_f32 v[10:11], v[204:205], v[208:209], v[10:11] op_sel:[1,0,0]
	v_pk_fma_f32 v[12:13], v[204:205], v[210:211], v[12:13] op_sel:[1,0,0]
	v_pk_fma_f32 v[6:7], v[206:207], v[208:209], v[6:7] op_sel_hi:[0,1,1]
	v_pk_fma_f32 v[8:9], v[206:207], v[210:211], v[8:9] op_sel_hi:[0,1,1]
	v_pk_fma_f32 v[2:3], v[206:207], v[208:209], v[2:3] op_sel:[1,0,0]
	v_pk_fma_f32 v[4:5], v[206:207], v[210:211], v[4:5] op_sel:[1,0,0]
	ds_read_b128 v[204:207], v220 offset:1088
	ds_read_b128 v[208:211], v221 offset:1088
	s_waitcnt lgkmcnt(2)
; __device__ __forceinline__ void dn1_item(const Params& p, int l, int item, unsigned char* lds) {
;     ...
;     mm64(B0, B1, wacc, ty, tx);
; #pragma unroll
;     for (int e = 0; e < 16; e += 4) { f32x4 w = {vv[e] * beti, vv[e + 1] * beti, vv[e + 2] * beti, vv[e + 3] * beti}; *(f32x4*)(B2 + i * DLD + d0 + e) = w; }
;     __syncthreads();
;     mm64(B0, B2, uacc, ty, tx);
	v_pk_fma_f32 v[14:15], v[212:213], v[216:217], v[14:15] op_sel_hi:[0,1,1]
	v_pk_fma_f32 v[16:17], v[212:213], v[218:219], v[16:17] op_sel_hi:[0,1,1]
	v_pk_fma_f32 v[10:11], v[212:213], v[216:217], v[10:11] op_sel:[1,0,0]
	v_pk_fma_f32 v[12:13], v[212:213], v[218:219], v[12:13] op_sel:[1,0,0]
	v_pk_fma_f32 v[6:7], v[214:215], v[216:217], v[6:7] op_sel_hi:[0,1,1]
	v_pk_fma_f32 v[8:9], v[214:215], v[218:219], v[8:9] op_sel_hi:[0,1,1]
	v_pk_fma_f32 v[2:3], v[214:215], v[216:217], v[2:3] op_sel:[1,0,0]
	v_pk_fma_f32 v[4:5], v[214:215], v[218:219], v[4:5] op_sel:[1,0,0]
	ds_read_b128 v[212:215], v220 offset:1360
	ds_read_b128 v[216:219], v221 offset:1360
	s_waitcnt lgkmcnt(2)
	v_pk_fma_f32 v[14:15], v[204:205], v[208:209], v[14:15] op_sel_hi:[0,1,1]
	v_pk_fma_f32 v[16:17], v[204:205], v[210:211], v[16:17] op_sel_hi:[0,1,1]
	v_pk_fma_f32 v[10:11], v[204:205], v[208:209], v[10:11] op_sel:[1,0,0]
	v_pk_fma_f32 v[12:13], v[204:205], v[210:211], v[12:13] op_sel:[1,0,0]
	v_pk_fma_f32 v[6:7], v[206:207], v[208:209], v[6:7] op_sel_hi:[0,1,1]
	v_pk_fma_f32 v[8:9], v[206:207], v[210:211], v[8:9] op_sel_hi:[0,1,1]
	v_pk_fma_f32 v[2:3], v[206:207], v[208:209], v[2:3] op_sel:[1,0,0]
	v_pk_fma_f32 v[4:5], v[206:207], v[210:211], v[4:5] op_sel:[1,0,0]
	ds_read_b128 v[204:207], v220 offset:1632
	ds_read_b128 v[208:211], v221 offset:1632
	s_waitcnt lgkmcnt(2)
	v_pk_fma_f32 v[14:15], v[212:213], v[216:217], v[14:15] op_sel_hi:[0,1,1]
	v_pk_fma_f32 v[16:17], v[212:213], v[218:219], v[16:17] op_sel_hi:[0,1,1]
	v_pk_fma_f32 v[10:11], v[212:213], v[216:217], v[10:11] op_sel:[1,0,0]
	v_pk_fma_f32 v[12:13], v[212:213], v[218:219], v[12:13] op_sel:[1,0,0]
	v_pk_fma_f32 v[6:7], v[214:215], v[216:217], v[6:7] op_sel_hi:[0,1,1]
	v_pk_fma_f32 v[8:9], v[214:215], v[218:219], v[8:9] op_sel_hi:[0,1,1]
	v_pk_fma_f32 v[2:3], v[214:215], v[216:217], v[2:3] op_sel:[1,0,0]
	v_pk_fma_f32 v[4:5], v[214:215], v[218:219], v[4:5] op_sel:[1,0,0]
	ds_read_b128 v[212:215], v220 offset:1904
	ds_read_b128 v[216:219], v221 offset:1904
	s_waitcnt lgkmcnt(2)
	v_pk_fma_f32 v[14:15], v[204:205], v[208:209], v[14:15] op_sel_hi:[0,1,1]
	v_pk_fma_f32 v[16:17], v[204:205], v[210:211], v[16:17] op_sel_hi:[0,1,1]
	v_pk_fma_f32 v[10:11], v[204:205], v[208:209], v[10:11] op_sel:[1,0,0]
	v_pk_fma_f32 v[12:13], v[204:205], v[210:211], v[12:13] op_sel:[1,0,0]
	v_pk_fma_f32 v[6:7], v[206:207], v[208:209], v[6:7] op_sel_hi:[0,1,1]
	v_pk_fma_f32 v[8:9], v[206:207], v[210:211], v[8:9] op_sel_hi:[0,1,1]
	v_pk_fma_f32 v[2:3], v[206:207], v[208:209], v[2:3] op_sel:[1,0,0]
	v_pk_fma_f32 v[4:5], v[206:207], v[210:211], v[4:5] op_sel:[1,0,0]
	s_addk_i32 s0, 0x880
	v_add_u32_e32 v220, s0, v51
	v_add_u32_e32 v221, s0, v95
	ds_read_b128 v[204:207], v220
	ds_read_b128 v[208:211], v221
	s_waitcnt lgkmcnt(2)
	v_pk_fma_f32 v[14:15], v[212:213], v[216:217], v[14:15] op_sel_hi:[0,1,1]
	v_pk_fma_f32 v[16:17], v[212:213], v[218:219], v[16:17] op_sel_hi:[0,1,1]
	v_pk_fma_f32 v[10:11], v[212:213], v[216:217], v[10:11] op_sel:[1,0,0]
	v_pk_fma_f32 v[12:13], v[212:213], v[218:219], v[12:13] op_sel:[1,0,0]
	v_pk_fma_f32 v[6:7], v[214:215], v[216:217], v[6:7] op_sel_hi:[0,1,1]
	v_pk_fma_f32 v[8:9], v[214:215], v[218:219], v[8:9] op_sel_hi:[0,1,1]
	v_pk_fma_f32 v[2:3], v[214:215], v[216:217], v[2:3] op_sel:[1,0,0]
	v_pk_fma_f32 v[4:5], v[214:215], v[218:219], v[4:5] op_sel:[1,0,0]
	s_cmpk_lg_i32 s0, 0x4400
	s_cbranch_scc1 .LBB0_634
	s_waitcnt lgkmcnt(0)
	v_pk_mul_f32 v[18:19], v[22:23], v[30:31]
	v_pk_mul_f32 v[20:21], v[24:25], v[78:79]
	v_pk_mul_f32 v[18:19], v[18:19], v[92:93] op_sel_hi:[1,0]
	v_pk_mul_f32 v[20:21], v[20:21], v[92:93] op_sel_hi:[1,0]
	ds_write_b128 v53, v[18:21] offset:34816
	v_pk_mul_f32 v[18:19], v[26:27], v[80:81]
	v_pk_mul_f32 v[20:21], v[28:29], v[82:83]
	v_pk_mul_f32 v[18:19], v[18:19], v[92:93] op_sel_hi:[1,0]
	v_pk_mul_f32 v[20:21], v[20:21], v[92:93] op_sel_hi:[1,0]
	ds_write_b128 v53, v[18:21] offset:34832
	v_pk_mul_f32 v[18:19], v[32:33], v[84:85]
	v_pk_mul_f32 v[20:21], v[70:71], v[86:87]
	v_pk_mul_f32 v[18:19], v[18:19], v[92:93] op_sel_hi:[1,0]
	v_pk_mul_f32 v[20:21], v[20:21], v[92:93] op_sel_hi:[1,0]
	ds_write_b128 v53, v[18:21] offset:34848
	v_pk_mul_f32 v[18:19], v[72:73], v[88:89]
	v_pk_mul_f32 v[20:21], v[74:75], v[90:91]
	v_pk_mul_f32 v[18:19], v[18:19], v[92:93] op_sel_hi:[1,0]
	v_pk_mul_f32 v[20:21], v[20:21], v[92:93] op_sel_hi:[1,0]
	ds_write_b128 v53, v[18:21] offset:34864
	v_readlane_b32 s0, v253, 51
	v_mov_b32_e32 v20, 0
	v_mov_b32_e32 v21, v20
	v_add_u32_e32 v70, s0, v94
	s_mov_b32 s0, 0
	v_mov_b32_e32 v30, v20
	v_mov_b32_e32 v31, v20
	v_mov_b32_e32 v32, v20
	v_mov_b32_e32 v33, v20
	v_mov_b32_e32 v26, v20
	v_mov_b32_e32 v27, v20
	v_mov_b32_e32 v28, v20
	v_mov_b32_e32 v29, v20
	v_mov_b32_e32 v22, v20
	v_mov_b32_e32 v23, v20
	v_mov_b32_e32 v24, v20
	v_mov_b32_e32 v25, v20
	v_mov_b32_e32 v18, v20
	v_mov_b32_e32 v19, v20
	s_waitcnt lgkmcnt(0)
	s_barrier
	v_add_u32_e32 v220, s0, v51
	v_add_u32_e32 v221, s0, v70
	ds_read_b128 v[204:207], v220
	ds_read_b128 v[208:211], v221
; __device__ __forceinline__ void mm64(const float* At, const float* B, float (&acc)[4][4], int ty, int tx) {
;     f32x2 c2[4][2];
; #pragma unroll
;     for (int rr = 0; rr < 4; ++rr) { c2[rr][0] = (f32x2){acc[rr][0], acc[rr][1]}; c2[rr][1] = (f32x2){acc[rr][2], acc[rr][3]}; }
; #pragma unroll 8
;     for (int k = 0; k < 64; ++k) {
;         const f32x4 a = *(const f32x4*)(At + k * DLD + 4 * ty);
;         const f32x4 b = *(const f32x4*)(B + k * DLD + 4 * tx);
;         const f32x2 b01 = {b.x, b.y}, b23 = {b.z, b.w};
; #pragma unroll
;         for (int rr = 0; rr < 4; ++rr) {
;             const f32x2 a2 = {a[rr], a[rr]};
;             c2[rr][0] = __builtin_elementwise_fma(a2, b01, c2[rr][0]);
;             c2[rr][1] = __builtin_elementwise_fma(a2, b23, c2[rr][1]);
;         }
;     }
; #pragma unroll
;     for (int rr = 0; rr < 4; ++rr) { acc[rr][0] = c2[rr][0].x; acc[rr][1] = c2[rr][0].y; acc[rr][2] = c2[rr][1].x; acc[rr][3] = c2[rr][1].y; }
.LBB0_636:
	ds_read_b128 v[212:215], v220 offset:272
	ds_read_b128 v[216:219], v221 offset:272
	s_waitcnt lgkmcnt(2)
	v_pk_fma_f32 v[30:31], v[204:205], v[208:209], v[30:31] op_sel_hi:[0,1,1]
	v_pk_fma_f32 v[32:33], v[204:205], v[210:211], v[32:33] op_sel_hi:[0,1,1]
	v_pk_fma_f32 v[26:27], v[204:205], v[208:209], v[26:27] op_sel:[1,0,0]
	v_pk_fma_f32 v[28:29], v[204:205], v[210:211], v[28:29] op_sel:[1,0,0]
	v_pk_fma_f32 v[22:23], v[206:207], v[208:209], v[22:23] op_sel_hi:[0,1,1]
	v_pk_fma_f32 v[24:25], v[206:207], v[210:211], v[24:25] op_sel_hi:[0,1,1]
	v_pk_fma_f32 v[18:19], v[206:207], v[208:209], v[18:19] op_sel:[1,0,0]
	v_pk_fma_f32 v[20:21], v[206:207], v[210:211], v[20:21] op_sel:[1,0,0]
	ds_read_b128 v[204:207], v220 offset:544
	ds_read_b128 v[208:211], v221 offset:544
	s_waitcnt lgkmcnt(2)
	v_pk_fma_f32 v[30:31], v[212:213], v[216:217], v[30:31] op_sel_hi:[0,1,1]
	v_pk_fma_f32 v[32:33], v[212:213], v[218:219], v[32:33] op_sel_hi:[0,1,1]
	v_pk_fma_f32 v[26:27], v[212:213], v[216:217], v[26:27] op_sel:[1,0,0]
	v_pk_fma_f32 v[28:29], v[212:213], v[218:219], v[28:29] op_sel:[1,0,0]
	v_pk_fma_f32 v[22:23], v[214:215], v[216:217], v[22:23] op_sel_hi:[0,1,1]
	v_pk_fma_f32 v[24:25], v[214:215], v[218:219], v[24:25] op_sel_hi:[0,1,1]
	v_pk_fma_f32 v[18:19], v[214:215], v[216:217], v[18:19] op_sel:[1,0,0]
	v_pk_fma_f32 v[20:21], v[214:215], v[218:219], v[20:21] op_sel:[1,0,0]
	ds_read_b128 v[212:215], v220 offset:816
	ds_read_b128 v[216:219], v221 offset:816
	s_waitcnt lgkmcnt(2)
	v_pk_fma_f32 v[30:31], v[204:205], v[208:209], v[30:31] op_sel_hi:[0,1,1]
	v_pk_fma_f32 v[32:33], v[204:205], v[210:211], v[32:33] op_sel_hi:[0,1,1]
	v_pk_fma_f32 v[26:27], v[204:205], v[208:209], v[26:27] op_sel:[1,0,0]
	v_pk_fma_f32 v[28:29], v[204:205], v[210:211], v[28:29] op_sel:[1,0,0]
	v_pk_fma_f32 v[22:23], v[206:207], v[208:209], v[22:23] op_sel_hi:[0,1,1]
	v_pk_fma_f32 v[24:25], v[206:207], v[210:211], v[24:25] op_sel_hi:[0,1,1]
	v_pk_fma_f32 v[18:19], v[206:207], v[208:209], v[18:19] op_sel:[1,0,0]
	v_pk_fma_f32 v[20:21], v[206:207], v[210:211], v[20:21] op_sel:[1,0,0]
	ds_read_b128 v[204:207], v220 offset:1088
	ds_read_b128 v[208:211], v221 offset:1088
	s_waitcnt lgkmcnt(2)
	v_pk_fma_f32 v[30:31], v[212:213], v[216:217], v[30:31] op_sel_hi:[0,1,1]
	v_pk_fma_f32 v[32:33], v[212:213], v[218:219], v[32:33] op_sel_hi:[0,1,1]
	v_pk_fma_f32 v[26:27], v[212:213], v[216:217], v[26:27] op_sel:[1,0,0]
	v_pk_fma_f32 v[28:29], v[212:213], v[218:219], v[28:29] op_sel:[1,0,0]
	v_pk_fma_f32 v[22:23], v[214:215], v[216:217], v[22:23] op_sel_hi:[0,1,1]
	v_pk_fma_f32 v[24:25], v[214:215], v[218:219], v[24:25] op_sel_hi:[0,1,1]
	v_pk_fma_f32 v[18:19], v[214:215], v[216:217], v[18:19] op_sel:[1,0,0]
	v_pk_fma_f32 v[20:21], v[214:215], v[218:219], v[20:21] op_sel:[1,0,0]
	ds_read_b128 v[212:215], v220 offset:1360
	ds_read_b128 v[216:219], v221 offset:1360
	s_waitcnt lgkmcnt(2)
	v_pk_fma_f32 v[30:31], v[204:205], v[208:209], v[30:31] op_sel_hi:[0,1,1]
	v_pk_fma_f32 v[32:33], v[204:205], v[210:211], v[32:33] op_sel_hi:[0,1,1]
	v_pk_fma_f32 v[26:27], v[204:205], v[208:209], v[26:27] op_sel:[1,0,0]
	v_pk_fma_f32 v[28:29], v[204:205], v[210:211], v[28:29] op_sel:[1,0,0]
	v_pk_fma_f32 v[22:23], v[206:207], v[208:209], v[22:23] op_sel_hi:[0,1,1]
	v_pk_fma_f32 v[24:25], v[206:207], v[210:211], v[24:25] op_sel_hi:[0,1,1]
	v_pk_fma_f32 v[18:19], v[206:207], v[208:209], v[18:19] op_sel:[1,0,0]
	v_pk_fma_f32 v[20:21], v[206:207], v[210:211], v[20:21] op_sel:[1,0,0]
	ds_read_b128 v[204:207], v220 offset:1632
	ds_read_b128 v[208:211], v221 offset:1632
	s_waitcnt lgkmcnt(2)
	v_pk_fma_f32 v[30:31], v[212:213], v[216:217], v[30:31] op_sel_hi:[0,1,1]
	v_pk_fma_f32 v[32:33], v[212:213], v[218:219], v[32:33] op_sel_hi:[0,1,1]
	v_pk_fma_f32 v[26:27], v[212:213], v[216:217], v[26:27] op_sel:[1,0,0]
	v_pk_fma_f32 v[28:29], v[212:213], v[218:219], v[28:29] op_sel:[1,0,0]
	v_pk_fma_f32 v[22:23], v[214:215], v[216:217], v[22:23] op_sel_hi:[0,1,1]
	v_pk_fma_f32 v[24:25], v[214:215], v[218:219], v[24:25] op_sel_hi:[0,1,1]
	v_pk_fma_f32 v[18:19], v[214:215], v[216:217], v[18:19] op_sel:[1,0,0]
	v_pk_fma_f32 v[20:21], v[214:215], v[218:219], v[20:21] op_sel:[1,0,0]
	ds_read_b128 v[212:215], v220 offset:1904
	ds_read_b128 v[216:219], v221 offset:1904
	s_waitcnt lgkmcnt(2)
	v_pk_fma_f32 v[30:31], v[204:205], v[208:209], v[30:31] op_sel_hi:[0,1,1]
	v_pk_fma_f32 v[32:33], v[204:205], v[210:211], v[32:33] op_sel_hi:[0,1,1]
	v_pk_fma_f32 v[26:27], v[204:205], v[208:209], v[26:27] op_sel:[1,0,0]
	v_pk_fma_f32 v[28:29], v[204:205], v[210:211], v[28:29] op_sel:[1,0,0]
	v_pk_fma_f32 v[22:23], v[206:207], v[208:209], v[22:23] op_sel_hi:[0,1,1]
	v_pk_fma_f32 v[24:25], v[206:207], v[210:211], v[24:25] op_sel_hi:[0,1,1]
	v_pk_fma_f32 v[18:19], v[206:207], v[208:209], v[18:19] op_sel:[1,0,0]
	v_pk_fma_f32 v[20:21], v[206:207], v[210:211], v[20:21] op_sel:[1,0,0]
	s_addk_i32 s0, 0x880
	v_add_u32_e32 v220, s0, v51
	v_add_u32_e32 v221, s0, v70
	ds_read_b128 v[204:207], v220
	ds_read_b128 v[208:211], v221
	s_waitcnt lgkmcnt(2)
	v_pk_fma_f32 v[30:31], v[212:213], v[216:217], v[30:31] op_sel_hi:[0,1,1]
	v_pk_fma_f32 v[32:33], v[212:213], v[218:219], v[32:33] op_sel_hi:[0,1,1]
	v_pk_fma_f32 v[26:27], v[212:213], v[216:217], v[26:27] op_sel:[1,0,0]
	v_pk_fma_f32 v[28:29], v[212:213], v[218:219], v[28:29] op_sel:[1,0,0]
	v_pk_fma_f32 v[22:23], v[214:215], v[216:217], v[22:23] op_sel_hi:[0,1,1]
	v_pk_fma_f32 v[24:25], v[214:215], v[218:219], v[24:25] op_sel_hi:[0,1,1]
	v_pk_fma_f32 v[18:19], v[214:215], v[216:217], v[18:19] op_sel:[1,0,0]
	v_pk_fma_f32 v[20:21], v[214:215], v[218:219], v[20:21] op_sel:[1,0,0]
	s_cmpk_lg_i32 s0, 0x4400
	s_cbranch_scc1 .LBB0_636
; #define ZERO44(a) { _Pragma("unroll") for (int _i = 0; _i < 4; ++_i) { _Pragma("unroll") for (int _j = 0; _j < 4; ++_j) a[_i][_j] = 0.f; } }
; __device__ __forceinline__ void dn1_item(const Params& p, int l, int item, unsigned char* lds) {
;     ...
; #pragma unroll
;     for (int rr = 0; rr < 4; ++rr) {
;         f32x4 w = {wacc[rr][0], wacc[rr][1], wacc[rr][2], wacc[rr][3]}; *(f32x4*)(B1 + (4 * ty + rr) * DLD + 4 * tx) = w;
;         f32x4 u = {uacc[rr][0], uacc[rr][1], uacc[rr][2], uacc[rr][3]}; *(f32x4*)(B2 + (4 * ty + rr) * DLD + 4 * tx) = u;
;     }
;     {
;         const float s = __expf(gcl - gci);
; #pragma unroll
;         for (int e = 0; e < 16; e += 4) { f32x4 w = {kn[e] * s, kn[e + 1] * s, kn[e + 2] * s, kn[e + 3] * s}; *(f32x4*)(B0 + i * DLD + d0 + e) = w; }
;     }
;     __syncthreads();
;     {
;         float a1[4][4]; ZERO44(a1);
;         mm64(B0, B1, a1, ty, tx);
	s_waitcnt lgkmcnt(0)
	v_lshl_add_u32 v71, v96, 2, v76
	s_movk_i32 s0, 0x110
	s_barrier
	ds_write_b128 v71, v[14:17] offset:17408
	ds_write_b128 v71, v[30:33] offset:34816
	v_mad_u64_u32 v[14:15], s[0:1], v103, s0, v[76:77]
	ds_write_b128 v14, v[10:13] offset:17408
	ds_write_b128 v14, v[26:29] offset:34816
	ds_write_b128 v14, v[6:9] offset:17680
	v_sub_f32_e32 v6, v106, v109
	v_mul_f32_e32 v6, 0x3fb8aa3b, v6
	v_exp_f32_e32 v6, v6
	ds_write_b128 v14, v[22:25] offset:35088
	ds_write_b128 v14, v[2:5] offset:17952
	ds_write_b128 v14, v[18:21] offset:35360
	s_mov_b32 s0, 0
	v_pk_mul_f32 v[4:5], v[68:69], v[6:7] op_sel_hi:[1,0]
	v_pk_mul_f32 v[2:3], v[66:67], v[6:7] op_sel_hi:[1,0]
	ds_write_b128 v53, v[2:5]
	v_pk_mul_f32 v[4:5], v[64:65], v[6:7] op_sel_hi:[1,0]
	v_pk_mul_f32 v[2:3], v[62:63], v[6:7] op_sel_hi:[1,0]
	ds_write_b128 v53, v[2:5] offset:16
	v_pk_mul_f32 v[4:5], v[60:61], v[6:7] op_sel_hi:[1,0]
	v_pk_mul_f32 v[2:3], v[58:59], v[6:7] op_sel_hi:[1,0]
	ds_write_b128 v53, v[2:5] offset:32
	v_pk_mul_f32 v[4:5], v[56:57], v[6:7] op_sel_hi:[1,0]
	v_pk_mul_f32 v[2:3], v[54:55], v[6:7] op_sel_hi:[1,0]
	ds_write_b128 v53, v[2:5] offset:48
	v_mov_b32_e32 v2, 0
	v_mov_b32_e32 v3, v2
	v_mov_b32_e32 v14, v2
	v_mov_b32_e32 v15, v2
	v_mov_b32_e32 v16, v2
	v_mov_b32_e32 v17, v2
	v_mov_b32_e32 v10, v2
	v_mov_b32_e32 v11, v2
	v_mov_b32_e32 v12, v2
	v_mov_b32_e32 v13, v2
	v_mov_b32_e32 v6, v2
	v_mov_b32_e32 v7, v2
	v_mov_b32_e32 v8, v2
	v_mov_b32_e32 v9, v2
	v_mov_b32_e32 v4, v2
	v_mov_b32_e32 v5, v2
	s_waitcnt lgkmcnt(0)
	s_barrier
	v_add_u32_e32 v220, s0, v51
	v_add_u32_e32 v221, s0, v95
	ds_read_b128 v[204:207], v220
	ds_read_b128 v[208:211], v221
.LBB0_638:
	ds_read_b128 v[212:215], v220 offset:272
	ds_read_b128 v[216:219], v221 offset:272
	s_waitcnt lgkmcnt(2)
	v_pk_fma_f32 v[14:15], v[204:205], v[208:209], v[14:15] op_sel_hi:[0,1,1]
	v_pk_fma_f32 v[16:17], v[204:205], v[210:211], v[16:17] op_sel_hi:[0,1,1]
	v_pk_fma_f32 v[10:11], v[204:205], v[208:209], v[10:11] op_sel:[1,0,0]
	v_pk_fma_f32 v[12:13], v[204:205], v[210:211], v[12:13] op_sel:[1,0,0]
	v_pk_fma_f32 v[6:7], v[206:207], v[208:209], v[6:7] op_sel_hi:[0,1,1]
	v_pk_fma_f32 v[8:9], v[206:207], v[210:211], v[8:9] op_sel_hi:[0,1,1]
	v_pk_fma_f32 v[4:5], v[206:207], v[208:209], v[4:5] op_sel:[1,0,0]
	v_pk_fma_f32 v[2:3], v[206:207], v[210:211], v[2:3] op_sel:[1,0,0]
	ds_read_b128 v[204:207], v220 offset:544
	ds_read_b128 v[208:211], v221 offset:544
	s_waitcnt lgkmcnt(2)
	v_pk_fma_f32 v[14:15], v[212:213], v[216:217], v[14:15] op_sel_hi:[0,1,1]
	v_pk_fma_f32 v[16:17], v[212:213], v[218:219], v[16:17] op_sel_hi:[0,1,1]
	v_pk_fma_f32 v[10:11], v[212:213], v[216:217], v[10:11] op_sel:[1,0,0]
	v_pk_fma_f32 v[12:13], v[212:213], v[218:219], v[12:13] op_sel:[1,0,0]
	v_pk_fma_f32 v[6:7], v[214:215], v[216:217], v[6:7] op_sel_hi:[0,1,1]
	v_pk_fma_f32 v[8:9], v[214:215], v[218:219], v[8:9] op_sel_hi:[0,1,1]
	v_pk_fma_f32 v[4:5], v[214:215], v[216:217], v[4:5] op_sel:[1,0,0]
	v_pk_fma_f32 v[2:3], v[214:215], v[218:219], v[2:3] op_sel:[1,0,0]
	ds_read_b128 v[212:215], v220 offset:816
	ds_read_b128 v[216:219], v221 offset:816
	s_waitcnt lgkmcnt(2)
	v_pk_fma_f32 v[14:15], v[204:205], v[208:209], v[14:15] op_sel_hi:[0,1,1]
	v_pk_fma_f32 v[16:17], v[204:205], v[210:211], v[16:17] op_sel_hi:[0,1,1]
	v_pk_fma_f32 v[10:11], v[204:205], v[208:209], v[10:11] op_sel:[1,0,0]
	v_pk_fma_f32 v[12:13], v[204:205], v[210:211], v[12:13] op_sel:[1,0,0]
	v_pk_fma_f32 v[6:7], v[206:207], v[208:209], v[6:7] op_sel_hi:[0,1,1]
	v_pk_fma_f32 v[8:9], v[206:207], v[210:211], v[8:9] op_sel_hi:[0,1,1]
	v_pk_fma_f32 v[4:5], v[206:207], v[208:209], v[4:5] op_sel:[1,0,0]
	v_pk_fma_f32 v[2:3], v[206:207], v[210:211], v[2:3] op_sel:[1,0,0]
	ds_read_b128 v[204:207], v220 offset:1088
	ds_read_b128 v[208:211], v221 offset:1088
	s_waitcnt lgkmcnt(2)
	v_pk_fma_f32 v[14:15], v[212:213], v[216:217], v[14:15] op_sel_hi:[0,1,1]
	v_pk_fma_f32 v[16:17], v[212:213], v[218:219], v[16:17] op_sel_hi:[0,1,1]
	v_pk_fma_f32 v[10:11], v[212:213], v[216:217], v[10:11] op_sel:[1,0,0]
	v_pk_fma_f32 v[12:13], v[212:213], v[218:219], v[12:13] op_sel:[1,0,0]
	v_pk_fma_f32 v[6:7], v[214:215], v[216:217], v[6:7] op_sel_hi:[0,1,1]
	v_pk_fma_f32 v[8:9], v[214:215], v[218:219], v[8:9] op_sel_hi:[0,1,1]
	v_pk_fma_f32 v[4:5], v[214:215], v[216:217], v[4:5] op_sel:[1,0,0]
	v_pk_fma_f32 v[2:3], v[214:215], v[218:219], v[2:3] op_sel:[1,0,0]
	ds_read_b128 v[212:215], v220 offset:1360
	ds_read_b128 v[216:219], v221 offset:1360
	s_waitcnt lgkmcnt(2)
	v_pk_fma_f32 v[14:15], v[204:205], v[208:209], v[14:15] op_sel_hi:[0,1,1]
	v_pk_fma_f32 v[16:17], v[204:205], v[210:211], v[16:17] op_sel_hi:[0,1,1]
	v_pk_fma_f32 v[10:11], v[204:205], v[208:209], v[10:11] op_sel:[1,0,0]
	v_pk_fma_f32 v[12:13], v[204:205], v[210:211], v[12:13] op_sel:[1,0,0]
	v_pk_fma_f32 v[6:7], v[206:207], v[208:209], v[6:7] op_sel_hi:[0,1,1]
	v_pk_fma_f32 v[8:9], v[206:207], v[210:211], v[8:9] op_sel_hi:[0,1,1]
	v_pk_fma_f32 v[4:5], v[206:207], v[208:209], v[4:5] op_sel:[1,0,0]
	v_pk_fma_f32 v[2:3], v[206:207], v[210:211], v[2:3] op_sel:[1,0,0]
	ds_read_b128 v[204:207], v220 offset:1632
	ds_read_b128 v[208:211], v221 offset:1632
	s_waitcnt lgkmcnt(2)
	v_pk_fma_f32 v[14:15], v[212:213], v[216:217], v[14:15] op_sel_hi:[0,1,1]
	v_pk_fma_f32 v[16:17], v[212:213], v[218:219], v[16:17] op_sel_hi:[0,1,1]
	v_pk_fma_f32 v[10:11], v[212:213], v[216:217], v[10:11] op_sel:[1,0,0]
	v_pk_fma_f32 v[12:13], v[212:213], v[218:219], v[12:13] op_sel:[1,0,0]
	v_pk_fma_f32 v[6:7], v[214:215], v[216:217], v[6:7] op_sel_hi:[0,1,1]
	v_pk_fma_f32 v[8:9], v[214:215], v[218:219], v[8:9] op_sel_hi:[0,1,1]
	v_pk_fma_f32 v[4:5], v[214:215], v[216:217], v[4:5] op_sel:[1,0,0]
	v_pk_fma_f32 v[2:3], v[214:215], v[218:219], v[2:3] op_sel:[1,0,0]
	ds_read_b128 v[212:215], v220 offset:1904
	ds_read_b128 v[216:219], v221 offset:1904
	s_waitcnt lgkmcnt(2)
; #define ZERO44(a) { _Pragma("unroll") for (int _i = 0; _i < 4; ++_i) { _Pragma("unroll") for (int _j = 0; _j < 4; ++_j) a[_i][_j] = 0.f; } }
; __device__ __forceinline__ void dn1_item(const Params& p, int l, int item, unsigned char* lds) {
;     ...
;         mm64(B0, B1, a1, ty, tx);
; #pragma unroll
;         for (int rr = 0; rr < 4; ++rr) {
;             f32x4 w;
; #pragma unroll
;             for (int cc = 0; cc < 4; ++cc) w[cc] = ((4 * ty + rr) == (4 * tx + cc) ? gl : 0.f) - a1[rr][cc];
;             *(f32x4*)(DNA + (4 * ty + rr) * 64 + 4 * tx) = w;
;         }
;         ZERO44(a1);
;         mm64(B0, B2, a1, ty, tx);
; #pragma unroll
	v_pk_fma_f32 v[14:15], v[204:205], v[208:209], v[14:15] op_sel_hi:[0,1,1]
	v_pk_fma_f32 v[16:17], v[204:205], v[210:211], v[16:17] op_sel_hi:[0,1,1]
	v_pk_fma_f32 v[10:11], v[204:205], v[208:209], v[10:11] op_sel:[1,0,0]
	v_pk_fma_f32 v[12:13], v[204:205], v[210:211], v[12:13] op_sel:[1,0,0]
	v_pk_fma_f32 v[6:7], v[206:207], v[208:209], v[6:7] op_sel_hi:[0,1,1]
	v_pk_fma_f32 v[8:9], v[206:207], v[210:211], v[8:9] op_sel_hi:[0,1,1]
	v_pk_fma_f32 v[4:5], v[206:207], v[208:209], v[4:5] op_sel:[1,0,0]
	v_pk_fma_f32 v[2:3], v[206:207], v[210:211], v[2:3] op_sel:[1,0,0]
	s_addk_i32 s0, 0x880
	v_add_u32_e32 v220, s0, v51
	v_add_u32_e32 v221, s0, v95
	ds_read_b128 v[204:207], v220
	ds_read_b128 v[208:211], v221
	s_waitcnt lgkmcnt(2)
	v_pk_fma_f32 v[14:15], v[212:213], v[216:217], v[14:15] op_sel_hi:[0,1,1]
	v_pk_fma_f32 v[16:17], v[212:213], v[218:219], v[16:17] op_sel_hi:[0,1,1]
	v_pk_fma_f32 v[10:11], v[212:213], v[216:217], v[10:11] op_sel:[1,0,0]
	v_pk_fma_f32 v[12:13], v[212:213], v[218:219], v[12:13] op_sel:[1,0,0]
	v_pk_fma_f32 v[6:7], v[214:215], v[216:217], v[6:7] op_sel_hi:[0,1,1]
	v_pk_fma_f32 v[8:9], v[214:215], v[218:219], v[8:9] op_sel_hi:[0,1,1]
	v_pk_fma_f32 v[4:5], v[214:215], v[216:217], v[4:5] op_sel:[1,0,0]
	v_pk_fma_f32 v[2:3], v[214:215], v[218:219], v[2:3] op_sel:[1,0,0]
	s_cmpk_lg_i32 s0, 0x4400
	s_cbranch_scc1 .LBB0_638
	s_waitcnt lgkmcnt(0)
	v_mul_f32_e32 v18, 0x3fb8aa3b, v106
	v_exp_f32_e32 v19, v18
	s_lshl_b32 s88, s21, 12
	s_lshl_b64 s[0:1], s[88:89], 2
	s_add_u32 s4, s3, s0
	s_addc_u32 s5, s8, s1
	v_lshlrev_b32_e32 v18, 8, v104
	v_cmp_eq_u32_e32 vcc, v105, v50
	v_lshl_add_u64 v[20:21], s[4:5], 0, v[0:1]
	v_pk_add_f32 v[16:17], v[16:17], 0 op_sel_hi:[1,0] neg_lo:[1,0] neg_hi:[1,0]
	v_cndmask_b32_e32 v0, 0, v19, vcc
	v_ashrrev_i32_e32 v19, 31, v18
	v_pk_add_f32 v[14:15], v[0:1], v[14:15] neg_lo:[0,1] neg_hi:[0,1]
	v_lshl_add_u64 v[20:21], v[18:19], 2, v[20:21]
	global_store_dwordx4 v[20:21], v[14:17], off
	v_pk_add_f32 v[6:7], v[6:7], 0 op_sel_hi:[1,0] neg_lo:[1,0] neg_hi:[1,0]
	v_pk_add_f32 v[8:9], v[0:1], v[8:9] neg_lo:[0,1] neg_hi:[0,1]
	v_mov_b32_e32 v14, v1
	v_mov_b32_e32 v15, v0
	global_store_dwordx4 v[20:21], v[6:9], off offset:512
	v_pk_add_f32 v[4:5], v[4:5], 0 op_sel_hi:[1,0] neg_lo:[1,0] neg_hi:[1,0]
	v_pk_add_f32 v[10:11], v[14:15], v[10:11] neg_lo:[0,1] neg_hi:[0,1]
	v_pk_add_f32 v[6:7], v[14:15], v[2:3] neg_lo:[0,1] neg_hi:[0,1]
	v_pk_add_f32 v[12:13], v[12:13], 0 op_sel_hi:[1,0] neg_lo:[1,0] neg_hi:[1,0]
	global_store_dwordx4 v[20:21], v[4:7], off offset:768
	s_mov_b32 s4, 0
	global_store_dwordx4 v[20:21], v[10:13], off offset:256
	v_mov_b32_e32 v4, 0
	v_mov_b32_e32 v5, v4
	v_mov_b32_e32 v14, v4
	v_mov_b32_e32 v15, v4
	v_mov_b32_e32 v16, v4
	v_mov_b32_e32 v17, v4
	v_mov_b32_e32 v10, v4
	v_mov_b32_e32 v11, v4
	v_mov_b32_e32 v12, v4
	v_mov_b32_e32 v13, v4
	v_mov_b32_e32 v6, v4
	v_mov_b32_e32 v7, v4
	v_mov_b32_e32 v8, v4
	v_mov_b32_e32 v9, v4
	v_mov_b32_e32 v2, v4
	v_mov_b32_e32 v3, v4
	v_add_u32_e32 v220, s4, v51
	v_add_u32_e32 v221, s4, v70
	ds_read_b128 v[204:207], v220
	ds_read_b128 v[208:211], v221
.LBB0_640:
	ds_read_b128 v[212:215], v220 offset:272
	ds_read_b128 v[216:219], v221 offset:272
	s_waitcnt lgkmcnt(2)
	v_pk_fma_f32 v[14:15], v[204:205], v[208:209], v[14:15] op_sel_hi:[0,1,1]
	v_pk_fma_f32 v[16:17], v[204:205], v[210:211], v[16:17] op_sel_hi:[0,1,1]
	v_pk_fma_f32 v[10:11], v[204:205], v[208:209], v[10:11] op_sel:[1,0,0]
	v_pk_fma_f32 v[12:13], v[204:205], v[210:211], v[12:13] op_sel:[1,0,0]
	v_pk_fma_f32 v[6:7], v[206:207], v[208:209], v[6:7] op_sel_hi:[0,1,1]
	v_pk_fma_f32 v[8:9], v[206:207], v[210:211], v[8:9] op_sel_hi:[0,1,1]
	v_pk_fma_f32 v[2:3], v[206:207], v[208:209], v[2:3] op_sel:[1,0,0]
	v_pk_fma_f32 v[4:5], v[206:207], v[210:211], v[4:5] op_sel:[1,0,0]
	ds_read_b128 v[204:207], v220 offset:544
	ds_read_b128 v[208:211], v221 offset:544
	s_waitcnt lgkmcnt(2)
	v_pk_fma_f32 v[14:15], v[212:213], v[216:217], v[14:15] op_sel_hi:[0,1,1]
	v_pk_fma_f32 v[16:17], v[212:213], v[218:219], v[16:17] op_sel_hi:[0,1,1]
	v_pk_fma_f32 v[10:11], v[212:213], v[216:217], v[10:11] op_sel:[1,0,0]
	v_pk_fma_f32 v[12:13], v[212:213], v[218:219], v[12:13] op_sel:[1,0,0]
	v_pk_fma_f32 v[6:7], v[214:215], v[216:217], v[6:7] op_sel_hi:[0,1,1]
	v_pk_fma_f32 v[8:9], v[214:215], v[218:219], v[8:9] op_sel_hi:[0,1,1]
	v_pk_fma_f32 v[2:3], v[214:215], v[216:217], v[2:3] op_sel:[1,0,0]
	v_pk_fma_f32 v[4:5], v[214:215], v[218:219], v[4:5] op_sel:[1,0,0]
	ds_read_b128 v[212:215], v220 offset:816
	ds_read_b128 v[216:219], v221 offset:816
	s_waitcnt lgkmcnt(2)
	v_pk_fma_f32 v[14:15], v[204:205], v[208:209], v[14:15] op_sel_hi:[0,1,1]
	v_pk_fma_f32 v[16:17], v[204:205], v[210:211], v[16:17] op_sel_hi:[0,1,1]
	v_pk_fma_f32 v[10:11], v[204:205], v[208:209], v[10:11] op_sel:[1,0,0]
	v_pk_fma_f32 v[12:13], v[204:205], v[210:211], v[12:13] op_sel:[1,0,0]
	v_pk_fma_f32 v[6:7], v[206:207], v[208:209], v[6:7] op_sel_hi:[0,1,1]
	v_pk_fma_f32 v[8:9], v[206:207], v[210:211], v[8:9] op_sel_hi:[0,1,1]
	v_pk_fma_f32 v[2:3], v[206:207], v[208:209], v[2:3] op_sel:[1,0,0]
	v_pk_fma_f32 v[4:5], v[206:207], v[210:211], v[4:5] op_sel:[1,0,0]
	ds_read_b128 v[204:207], v220 offset:1088
	ds_read_b128 v[208:211], v221 offset:1088
	s_waitcnt lgkmcnt(2)
	v_pk_fma_f32 v[14:15], v[212:213], v[216:217], v[14:15] op_sel_hi:[0,1,1]
	v_pk_fma_f32 v[16:17], v[212:213], v[218:219], v[16:17] op_sel_hi:[0,1,1]
	v_pk_fma_f32 v[10:11], v[212:213], v[216:217], v[10:11] op_sel:[1,0,0]
	v_pk_fma_f32 v[12:13], v[212:213], v[218:219], v[12:13] op_sel:[1,0,0]
	v_pk_fma_f32 v[6:7], v[214:215], v[216:217], v[6:7] op_sel_hi:[0,1,1]
	v_pk_fma_f32 v[8:9], v[214:215], v[218:219], v[8:9] op_sel_hi:[0,1,1]
	v_pk_fma_f32 v[2:3], v[214:215], v[216:217], v[2:3] op_sel:[1,0,0]
	v_pk_fma_f32 v[4:5], v[214:215], v[218:219], v[4:5] op_sel:[1,0,0]
	ds_read_b128 v[212:215], v220 offset:1360
	ds_read_b128 v[216:219], v221 offset:1360
	s_waitcnt lgkmcnt(2)
; #define ZERO44(a) { _Pragma("unroll") for (int _i = 0; _i < 4; ++_i) { _Pragma("unroll") for (int _j = 0; _j < 4; ++_j) a[_i][_j] = 0.f; } }
; __device__ __forceinline__ void dn1_item(const Params& p, int l, int item, unsigned char* lds) {
;     ...
;         mm64(B0, B2, a1, ty, tx);
; #pragma unroll
;         for (int rr = 0; rr < 4; ++rr) { f32x4 w = {a1[rr][0], a1[rr][1], a1[rr][2], a1[rr][3]}; *(f32x4*)(DNB + (4 * ty + rr) * 64 + 4 * tx) = w; }
;     }
;     float hacc[4][4]; ZERO44(hacc);
;     mm64(B1, B3, hacc, ty, tx);
	v_pk_fma_f32 v[14:15], v[204:205], v[208:209], v[14:15] op_sel_hi:[0,1,1]
	v_pk_fma_f32 v[16:17], v[204:205], v[210:211], v[16:17] op_sel_hi:[0,1,1]
	v_pk_fma_f32 v[10:11], v[204:205], v[208:209], v[10:11] op_sel:[1,0,0]
	v_pk_fma_f32 v[12:13], v[204:205], v[210:211], v[12:13] op_sel:[1,0,0]
	v_pk_fma_f32 v[6:7], v[206:207], v[208:209], v[6:7] op_sel_hi:[0,1,1]
	v_pk_fma_f32 v[8:9], v[206:207], v[210:211], v[8:9] op_sel_hi:[0,1,1]
	v_pk_fma_f32 v[2:3], v[206:207], v[208:209], v[2:3] op_sel:[1,0,0]
	v_pk_fma_f32 v[4:5], v[206:207], v[210:211], v[4:5] op_sel:[1,0,0]
	ds_read_b128 v[204:207], v220 offset:1632
	ds_read_b128 v[208:211], v221 offset:1632
	s_waitcnt lgkmcnt(2)
	v_pk_fma_f32 v[14:15], v[212:213], v[216:217], v[14:15] op_sel_hi:[0,1,1]
	v_pk_fma_f32 v[16:17], v[212:213], v[218:219], v[16:17] op_sel_hi:[0,1,1]
	v_pk_fma_f32 v[10:11], v[212:213], v[216:217], v[10:11] op_sel:[1,0,0]
	v_pk_fma_f32 v[12:13], v[212:213], v[218:219], v[12:13] op_sel:[1,0,0]
	v_pk_fma_f32 v[6:7], v[214:215], v[216:217], v[6:7] op_sel_hi:[0,1,1]
	v_pk_fma_f32 v[8:9], v[214:215], v[218:219], v[8:9] op_sel_hi:[0,1,1]
	v_pk_fma_f32 v[2:3], v[214:215], v[216:217], v[2:3] op_sel:[1,0,0]
	v_pk_fma_f32 v[4:5], v[214:215], v[218:219], v[4:5] op_sel:[1,0,0]
	ds_read_b128 v[212:215], v220 offset:1904
	ds_read_b128 v[216:219], v221 offset:1904
	s_waitcnt lgkmcnt(2)
	v_pk_fma_f32 v[14:15], v[204:205], v[208:209], v[14:15] op_sel_hi:[0,1,1]
	v_pk_fma_f32 v[16:17], v[204:205], v[210:211], v[16:17] op_sel_hi:[0,1,1]
	v_pk_fma_f32 v[10:11], v[204:205], v[208:209], v[10:11] op_sel:[1,0,0]
	v_pk_fma_f32 v[12:13], v[204:205], v[210:211], v[12:13] op_sel:[1,0,0]
	v_pk_fma_f32 v[6:7], v[206:207], v[208:209], v[6:7] op_sel_hi:[0,1,1]
	v_pk_fma_f32 v[8:9], v[206:207], v[210:211], v[8:9] op_sel_hi:[0,1,1]
	v_pk_fma_f32 v[2:3], v[206:207], v[208:209], v[2:3] op_sel:[1,0,0]
	v_pk_fma_f32 v[4:5], v[206:207], v[210:211], v[4:5] op_sel:[1,0,0]
	s_addk_i32 s4, 0x880
	v_add_u32_e32 v220, s4, v51
	v_add_u32_e32 v221, s4, v70
	ds_read_b128 v[204:207], v220
	ds_read_b128 v[208:211], v221
	s_waitcnt lgkmcnt(2)
	v_pk_fma_f32 v[14:15], v[212:213], v[216:217], v[14:15] op_sel_hi:[0,1,1]
	v_pk_fma_f32 v[16:17], v[212:213], v[218:219], v[16:17] op_sel_hi:[0,1,1]
	v_pk_fma_f32 v[10:11], v[212:213], v[216:217], v[10:11] op_sel:[1,0,0]
	v_pk_fma_f32 v[12:13], v[212:213], v[218:219], v[12:13] op_sel:[1,0,0]
	v_pk_fma_f32 v[6:7], v[214:215], v[216:217], v[6:7] op_sel_hi:[0,1,1]
	v_pk_fma_f32 v[8:9], v[214:215], v[218:219], v[8:9] op_sel_hi:[0,1,1]
	v_pk_fma_f32 v[2:3], v[214:215], v[216:217], v[2:3] op_sel:[1,0,0]
	v_pk_fma_f32 v[4:5], v[214:215], v[218:219], v[4:5] op_sel:[1,0,0]
	s_cmpk_lg_i32 s4, 0x4400
	s_cbranch_scc1 .LBB0_640
	s_waitcnt lgkmcnt(0)
	s_add_u32 s4, s9, s0
	s_addc_u32 s5, s10, s1
	v_lshlrev_b32_e32 v0, 2, v50
	v_lshl_add_u64 v[20:21], s[4:5], 0, v[0:1]
	v_lshl_add_u64 v[20:21], v[18:19], 2, v[20:21]
	global_store_dwordx4 v[20:21], v[14:17], off
	global_store_dwordx4 v[20:21], v[10:13], off offset:256
	global_store_dwordx4 v[20:21], v[6:9], off offset:512
	global_store_dwordx4 v[20:21], v[2:5], off offset:768
	v_readlane_b32 s4, v253, 52
	v_mov_b32_e32 v20, 0
	v_mov_b32_e32 v21, v20
	v_add_u32_e32 v2, s4, v94
	s_mov_b32 s4, 0
	v_mov_b32_e32 v32, v20
	v_mov_b32_e32 v33, v20
	v_mov_b32_e32 v50, v20
	v_mov_b32_e32 v51, v20
	v_mov_b32_e32 v28, v20
	v_mov_b32_e32 v29, v20
	v_mov_b32_e32 v30, v20
	v_mov_b32_e32 v31, v20
	v_mov_b32_e32 v24, v20
	v_mov_b32_e32 v25, v20
	v_mov_b32_e32 v26, v20
	v_mov_b32_e32 v27, v20
	v_mov_b32_e32 v22, v20
	v_mov_b32_e32 v23, v20
	v_add_u32_e32 v220, s4, v93
	v_add_u32_e32 v221, s4, v2
	ds_read_b128 v[204:207], v220
	ds_read_b128 v[208:211], v221
.LBB0_642:
	ds_read_b128 v[212:215], v220 offset:272
	ds_read_b128 v[216:219], v221 offset:272
	s_waitcnt lgkmcnt(2)
	v_pk_fma_f32 v[32:33], v[204:205], v[208:209], v[32:33] op_sel_hi:[0,1,1]
	v_pk_fma_f32 v[50:51], v[204:205], v[210:211], v[50:51] op_sel_hi:[0,1,1]
	v_pk_fma_f32 v[28:29], v[204:205], v[208:209], v[28:29] op_sel:[1,0,0]
	v_pk_fma_f32 v[30:31], v[204:205], v[210:211], v[30:31] op_sel:[1,0,0]
	v_pk_fma_f32 v[24:25], v[206:207], v[208:209], v[24:25] op_sel_hi:[0,1,1]
	v_pk_fma_f32 v[26:27], v[206:207], v[210:211], v[26:27] op_sel_hi:[0,1,1]
	v_pk_fma_f32 v[22:23], v[206:207], v[208:209], v[22:23] op_sel:[1,0,0]
	v_pk_fma_f32 v[20:21], v[206:207], v[210:211], v[20:21] op_sel:[1,0,0]
	ds_read_b128 v[204:207], v220 offset:544
	ds_read_b128 v[208:211], v221 offset:544
	s_waitcnt lgkmcnt(2)
	v_pk_fma_f32 v[32:33], v[212:213], v[216:217], v[32:33] op_sel_hi:[0,1,1]
	v_pk_fma_f32 v[50:51], v[212:213], v[218:219], v[50:51] op_sel_hi:[0,1,1]
	v_pk_fma_f32 v[28:29], v[212:213], v[216:217], v[28:29] op_sel:[1,0,0]
	v_pk_fma_f32 v[30:31], v[212:213], v[218:219], v[30:31] op_sel:[1,0,0]
	v_pk_fma_f32 v[24:25], v[214:215], v[216:217], v[24:25] op_sel_hi:[0,1,1]
	v_pk_fma_f32 v[26:27], v[214:215], v[218:219], v[26:27] op_sel_hi:[0,1,1]
	v_pk_fma_f32 v[22:23], v[214:215], v[216:217], v[22:23] op_sel:[1,0,0]
	v_pk_fma_f32 v[20:21], v[214:215], v[218:219], v[20:21] op_sel:[1,0,0]
	ds_read_b128 v[212:215], v220 offset:816
	ds_read_b128 v[216:219], v221 offset:816
	s_waitcnt lgkmcnt(2)
	v_pk_fma_f32 v[32:33], v[204:205], v[208:209], v[32:33] op_sel_hi:[0,1,1]
	v_pk_fma_f32 v[50:51], v[204:205], v[210:211], v[50:51] op_sel_hi:[0,1,1]
	v_pk_fma_f32 v[28:29], v[204:205], v[208:209], v[28:29] op_sel:[1,0,0]
	v_pk_fma_f32 v[30:31], v[204:205], v[210:211], v[30:31] op_sel:[1,0,0]
	v_pk_fma_f32 v[24:25], v[206:207], v[208:209], v[24:25] op_sel_hi:[0,1,1]
	v_pk_fma_f32 v[26:27], v[206:207], v[210:211], v[26:27] op_sel_hi:[0,1,1]
	v_pk_fma_f32 v[22:23], v[206:207], v[208:209], v[22:23] op_sel:[1,0,0]
	v_pk_fma_f32 v[20:21], v[206:207], v[210:211], v[20:21] op_sel:[1,0,0]
	ds_read_b128 v[204:207], v220 offset:1088
	ds_read_b128 v[208:211], v221 offset:1088
	s_waitcnt lgkmcnt(2)
; #define ZERO44(a) { _Pragma("unroll") for (int _i = 0; _i < 4; ++_i) { _Pragma("unroll") for (int _j = 0; _j < 4; ++_j) a[_i][_j] = 0.f; } }
; __device__ __forceinline__ void dn1_item(const Params& p, int l, int item, unsigned char* lds) {
;     ...
;     mm64(B1, B3, hacc, ty, tx);
;     {
;         float a1[4][4]; ZERO44(a1);
;         mm64(B3, B2, a1, ty, tx);
	v_pk_fma_f32 v[32:33], v[212:213], v[216:217], v[32:33] op_sel_hi:[0,1,1]
	v_pk_fma_f32 v[50:51], v[212:213], v[218:219], v[50:51] op_sel_hi:[0,1,1]
	v_pk_fma_f32 v[28:29], v[212:213], v[216:217], v[28:29] op_sel:[1,0,0]
	v_pk_fma_f32 v[30:31], v[212:213], v[218:219], v[30:31] op_sel:[1,0,0]
	v_pk_fma_f32 v[24:25], v[214:215], v[216:217], v[24:25] op_sel_hi:[0,1,1]
	v_pk_fma_f32 v[26:27], v[214:215], v[218:219], v[26:27] op_sel_hi:[0,1,1]
	v_pk_fma_f32 v[22:23], v[214:215], v[216:217], v[22:23] op_sel:[1,0,0]
	v_pk_fma_f32 v[20:21], v[214:215], v[218:219], v[20:21] op_sel:[1,0,0]
	ds_read_b128 v[212:215], v220 offset:1360
	ds_read_b128 v[216:219], v221 offset:1360
	s_waitcnt lgkmcnt(2)
	v_pk_fma_f32 v[32:33], v[204:205], v[208:209], v[32:33] op_sel_hi:[0,1,1]
	v_pk_fma_f32 v[50:51], v[204:205], v[210:211], v[50:51] op_sel_hi:[0,1,1]
	v_pk_fma_f32 v[28:29], v[204:205], v[208:209], v[28:29] op_sel:[1,0,0]
	v_pk_fma_f32 v[30:31], v[204:205], v[210:211], v[30:31] op_sel:[1,0,0]
	v_pk_fma_f32 v[24:25], v[206:207], v[208:209], v[24:25] op_sel_hi:[0,1,1]
	v_pk_fma_f32 v[26:27], v[206:207], v[210:211], v[26:27] op_sel_hi:[0,1,1]
	v_pk_fma_f32 v[22:23], v[206:207], v[208:209], v[22:23] op_sel:[1,0,0]
	v_pk_fma_f32 v[20:21], v[206:207], v[210:211], v[20:21] op_sel:[1,0,0]
	ds_read_b128 v[204:207], v220 offset:1632
	ds_read_b128 v[208:211], v221 offset:1632
	s_waitcnt lgkmcnt(2)
	v_pk_fma_f32 v[32:33], v[212:213], v[216:217], v[32:33] op_sel_hi:[0,1,1]
	v_pk_fma_f32 v[50:51], v[212:213], v[218:219], v[50:51] op_sel_hi:[0,1,1]
	v_pk_fma_f32 v[28:29], v[212:213], v[216:217], v[28:29] op_sel:[1,0,0]
	v_pk_fma_f32 v[30:31], v[212:213], v[218:219], v[30:31] op_sel:[1,0,0]
	v_pk_fma_f32 v[24:25], v[214:215], v[216:217], v[24:25] op_sel_hi:[0,1,1]
	v_pk_fma_f32 v[26:27], v[214:215], v[218:219], v[26:27] op_sel_hi:[0,1,1]
	v_pk_fma_f32 v[22:23], v[214:215], v[216:217], v[22:23] op_sel:[1,0,0]
	v_pk_fma_f32 v[20:21], v[214:215], v[218:219], v[20:21] op_sel:[1,0,0]
	ds_read_b128 v[212:215], v220 offset:1904
	ds_read_b128 v[216:219], v221 offset:1904
	s_waitcnt lgkmcnt(2)
	v_pk_fma_f32 v[32:33], v[204:205], v[208:209], v[32:33] op_sel_hi:[0,1,1]
	v_pk_fma_f32 v[50:51], v[204:205], v[210:211], v[50:51] op_sel_hi:[0,1,1]
	v_pk_fma_f32 v[28:29], v[204:205], v[208:209], v[28:29] op_sel:[1,0,0]
	v_pk_fma_f32 v[30:31], v[204:205], v[210:211], v[30:31] op_sel:[1,0,0]
	v_pk_fma_f32 v[24:25], v[206:207], v[208:209], v[24:25] op_sel_hi:[0,1,1]
	v_pk_fma_f32 v[26:27], v[206:207], v[210:211], v[26:27] op_sel_hi:[0,1,1]
	v_pk_fma_f32 v[22:23], v[206:207], v[208:209], v[22:23] op_sel:[1,0,0]
	v_pk_fma_f32 v[20:21], v[206:207], v[210:211], v[20:21] op_sel:[1,0,0]
	s_addk_i32 s4, 0x880
	v_add_u32_e32 v220, s4, v93
	v_add_u32_e32 v221, s4, v2
	ds_read_b128 v[204:207], v220
	ds_read_b128 v[208:211], v221
	s_waitcnt lgkmcnt(2)
	v_pk_fma_f32 v[32:33], v[212:213], v[216:217], v[32:33] op_sel_hi:[0,1,1]
	v_pk_fma_f32 v[50:51], v[212:213], v[218:219], v[50:51] op_sel_hi:[0,1,1]
	v_pk_fma_f32 v[28:29], v[212:213], v[216:217], v[28:29] op_sel:[1,0,0]
	v_pk_fma_f32 v[30:31], v[212:213], v[218:219], v[30:31] op_sel:[1,0,0]
	v_pk_fma_f32 v[24:25], v[214:215], v[216:217], v[24:25] op_sel_hi:[0,1,1]
	v_pk_fma_f32 v[26:27], v[214:215], v[218:219], v[26:27] op_sel_hi:[0,1,1]
	v_pk_fma_f32 v[22:23], v[214:215], v[216:217], v[22:23] op_sel:[1,0,0]
	v_pk_fma_f32 v[20:21], v[214:215], v[218:219], v[20:21] op_sel:[1,0,0]
	s_cmpk_lg_i32 s4, 0x4400
	s_cbranch_scc1 .LBB0_642
	s_waitcnt lgkmcnt(0)
	v_readlane_b32 s4, v253, 52
	v_mov_b32_e32 v4, 0
	v_mov_b32_e32 v5, v4
	v_add_u32_e32 v54, s4, v77
	s_mov_b32 s4, 0
	v_mov_b32_e32 v14, v4
	v_mov_b32_e32 v15, v4
	v_mov_b32_e32 v16, v4
	v_mov_b32_e32 v17, v4
	v_mov_b32_e32 v10, v4
	v_mov_b32_e32 v11, v4
	v_mov_b32_e32 v12, v4
	v_mov_b32_e32 v13, v4
	v_mov_b32_e32 v6, v4
	v_mov_b32_e32 v7, v4
	v_mov_b32_e32 v8, v4
	v_mov_b32_e32 v9, v4
	v_mov_b32_e32 v2, v4
	v_mov_b32_e32 v3, v4
	v_add_u32_e32 v220, s4, v54
	v_add_u32_e32 v221, s4, v70
	ds_read_b128 v[204:207], v220
	ds_read_b128 v[208:211], v221
.LBB0_644:
	ds_read_b128 v[212:215], v220 offset:272
	ds_read_b128 v[216:219], v221 offset:272
	s_waitcnt lgkmcnt(2)
	v_pk_fma_f32 v[14:15], v[204:205], v[208:209], v[14:15] op_sel_hi:[0,1,1]
	v_pk_fma_f32 v[16:17], v[204:205], v[210:211], v[16:17] op_sel_hi:[0,1,1]
	v_pk_fma_f32 v[10:11], v[204:205], v[208:209], v[10:11] op_sel:[1,0,0]
	v_pk_fma_f32 v[12:13], v[204:205], v[210:211], v[12:13] op_sel:[1,0,0]
	v_pk_fma_f32 v[6:7], v[206:207], v[208:209], v[6:7] op_sel_hi:[0,1,1]
	v_pk_fma_f32 v[8:9], v[206:207], v[210:211], v[8:9] op_sel_hi:[0,1,1]
	v_pk_fma_f32 v[2:3], v[206:207], v[208:209], v[2:3] op_sel:[1,0,0]
	v_pk_fma_f32 v[4:5], v[206:207], v[210:211], v[4:5] op_sel:[1,0,0]
	ds_read_b128 v[204:207], v220 offset:544
	ds_read_b128 v[208:211], v221 offset:544
	s_waitcnt lgkmcnt(2)
	v_pk_fma_f32 v[14:15], v[212:213], v[216:217], v[14:15] op_sel_hi:[0,1,1]
	v_pk_fma_f32 v[16:17], v[212:213], v[218:219], v[16:17] op_sel_hi:[0,1,1]
	v_pk_fma_f32 v[10:11], v[212:213], v[216:217], v[10:11] op_sel:[1,0,0]
	v_pk_fma_f32 v[12:13], v[212:213], v[218:219], v[12:13] op_sel:[1,0,0]
	v_pk_fma_f32 v[6:7], v[214:215], v[216:217], v[6:7] op_sel_hi:[0,1,1]
	v_pk_fma_f32 v[8:9], v[214:215], v[218:219], v[8:9] op_sel_hi:[0,1,1]
	v_pk_fma_f32 v[2:3], v[214:215], v[216:217], v[2:3] op_sel:[1,0,0]
	v_pk_fma_f32 v[4:5], v[214:215], v[218:219], v[4:5] op_sel:[1,0,0]
	ds_read_b128 v[212:215], v220 offset:816
	ds_read_b128 v[216:219], v221 offset:816
	s_waitcnt lgkmcnt(2)
; __device__ __forceinline__ void dn1_item(const Params& p, int l, int item, unsigned char* lds) {
;     ...
;         mm64(B3, B2, a1, ty, tx);
; #pragma unroll
;         for (int rr = 0; rr < 4; ++rr) { f32x4 w = {a1[rr][0], a1[rr][1], a1[rr][2], a1[rr][3]}; *(f32x4*)(DNO + (4 * ty + rr) * 64 + 4 * tx) = w; }
;     }
;     __syncthreads();
;     {
;         const float s = __expf(gci);
; #pragma unroll
;         for (int e = 0; e < 16; e += 4) { f32x4 w = {qn[e] * s, qn[e + 1] * s, qn[e + 2] * s, qn[e + 3] * s}; *(f32x4*)(B0 + i * DLD + d0 + e) = w; }
;     }
;     __syncthreads();
; #pragma unroll
;     for (int rr = 0; rr < 4; ++rr) {
;         f32x4 w;
; #pragma unroll
;         for (int cc = 0; cc < 4; ++cc) w[cc] = B0[(4 * tx + cc) * DLD + 4 * ty + rr] - hacc[rr][cc];
;         *(f32x4*)(DNQ + (4 * ty + rr) * 64 + 4 * tx) = w;
;     }
;     __syncthreads();
	v_pk_fma_f32 v[14:15], v[204:205], v[208:209], v[14:15] op_sel_hi:[0,1,1]
	v_pk_fma_f32 v[16:17], v[204:205], v[210:211], v[16:17] op_sel_hi:[0,1,1]
	v_pk_fma_f32 v[10:11], v[204:205], v[208:209], v[10:11] op_sel:[1,0,0]
	v_pk_fma_f32 v[12:13], v[204:205], v[210:211], v[12:13] op_sel:[1,0,0]
	v_pk_fma_f32 v[6:7], v[206:207], v[208:209], v[6:7] op_sel_hi:[0,1,1]
	v_pk_fma_f32 v[8:9], v[206:207], v[210:211], v[8:9] op_sel_hi:[0,1,1]
	v_pk_fma_f32 v[2:3], v[206:207], v[208:209], v[2:3] op_sel:[1,0,0]
	v_pk_fma_f32 v[4:5], v[206:207], v[210:211], v[4:5] op_sel:[1,0,0]
	ds_read_b128 v[204:207], v220 offset:1088
	ds_read_b128 v[208:211], v221 offset:1088
	s_waitcnt lgkmcnt(2)
	v_pk_fma_f32 v[14:15], v[212:213], v[216:217], v[14:15] op_sel_hi:[0,1,1]
	v_pk_fma_f32 v[16:17], v[212:213], v[218:219], v[16:17] op_sel_hi:[0,1,1]
	v_pk_fma_f32 v[10:11], v[212:213], v[216:217], v[10:11] op_sel:[1,0,0]
	v_pk_fma_f32 v[12:13], v[212:213], v[218:219], v[12:13] op_sel:[1,0,0]
	v_pk_fma_f32 v[6:7], v[214:215], v[216:217], v[6:7] op_sel_hi:[0,1,1]
	v_pk_fma_f32 v[8:9], v[214:215], v[218:219], v[8:9] op_sel_hi:[0,1,1]
	v_pk_fma_f32 v[2:3], v[214:215], v[216:217], v[2:3] op_sel:[1,0,0]
	v_pk_fma_f32 v[4:5], v[214:215], v[218:219], v[4:5] op_sel:[1,0,0]
	ds_read_b128 v[212:215], v220 offset:1360
	ds_read_b128 v[216:219], v221 offset:1360
	s_waitcnt lgkmcnt(2)
	v_pk_fma_f32 v[14:15], v[204:205], v[208:209], v[14:15] op_sel_hi:[0,1,1]
	v_pk_fma_f32 v[16:17], v[204:205], v[210:211], v[16:17] op_sel_hi:[0,1,1]
	v_pk_fma_f32 v[10:11], v[204:205], v[208:209], v[10:11] op_sel:[1,0,0]
	v_pk_fma_f32 v[12:13], v[204:205], v[210:211], v[12:13] op_sel:[1,0,0]
	v_pk_fma_f32 v[6:7], v[206:207], v[208:209], v[6:7] op_sel_hi:[0,1,1]
	v_pk_fma_f32 v[8:9], v[206:207], v[210:211], v[8:9] op_sel_hi:[0,1,1]
	v_pk_fma_f32 v[2:3], v[206:207], v[208:209], v[2:3] op_sel:[1,0,0]
	v_pk_fma_f32 v[4:5], v[206:207], v[210:211], v[4:5] op_sel:[1,0,0]
	ds_read_b128 v[204:207], v220 offset:1632
	ds_read_b128 v[208:211], v221 offset:1632
	s_waitcnt lgkmcnt(2)
	v_pk_fma_f32 v[14:15], v[212:213], v[216:217], v[14:15] op_sel_hi:[0,1,1]
	v_pk_fma_f32 v[16:17], v[212:213], v[218:219], v[16:17] op_sel_hi:[0,1,1]
	v_pk_fma_f32 v[10:11], v[212:213], v[216:217], v[10:11] op_sel:[1,0,0]
	v_pk_fma_f32 v[12:13], v[212:213], v[218:219], v[12:13] op_sel:[1,0,0]
	v_pk_fma_f32 v[6:7], v[214:215], v[216:217], v[6:7] op_sel_hi:[0,1,1]
	v_pk_fma_f32 v[8:9], v[214:215], v[218:219], v[8:9] op_sel_hi:[0,1,1]
	v_pk_fma_f32 v[2:3], v[214:215], v[216:217], v[2:3] op_sel:[1,0,0]
	v_pk_fma_f32 v[4:5], v[214:215], v[218:219], v[4:5] op_sel:[1,0,0]
	ds_read_b128 v[212:215], v220 offset:1904
	ds_read_b128 v[216:219], v221 offset:1904
	s_waitcnt lgkmcnt(2)
	v_pk_fma_f32 v[14:15], v[204:205], v[208:209], v[14:15] op_sel_hi:[0,1,1]
	v_pk_fma_f32 v[16:17], v[204:205], v[210:211], v[16:17] op_sel_hi:[0,1,1]
	v_pk_fma_f32 v[10:11], v[204:205], v[208:209], v[10:11] op_sel:[1,0,0]
	v_pk_fma_f32 v[12:13], v[204:205], v[210:211], v[12:13] op_sel:[1,0,0]
	v_pk_fma_f32 v[6:7], v[206:207], v[208:209], v[6:7] op_sel_hi:[0,1,1]
	v_pk_fma_f32 v[8:9], v[206:207], v[210:211], v[8:9] op_sel_hi:[0,1,1]
	v_pk_fma_f32 v[2:3], v[206:207], v[208:209], v[2:3] op_sel:[1,0,0]
	v_pk_fma_f32 v[4:5], v[206:207], v[210:211], v[4:5] op_sel:[1,0,0]
	s_addk_i32 s4, 0x880
	v_add_u32_e32 v220, s4, v54
	v_add_u32_e32 v221, s4, v70
	ds_read_b128 v[204:207], v220
	ds_read_b128 v[208:211], v221
	s_waitcnt lgkmcnt(2)
	v_pk_fma_f32 v[14:15], v[212:213], v[216:217], v[14:15] op_sel_hi:[0,1,1]
	v_pk_fma_f32 v[16:17], v[212:213], v[218:219], v[16:17] op_sel_hi:[0,1,1]
	v_pk_fma_f32 v[10:11], v[212:213], v[216:217], v[10:11] op_sel:[1,0,0]
	v_pk_fma_f32 v[12:13], v[212:213], v[218:219], v[12:13] op_sel:[1,0,0]
	v_pk_fma_f32 v[6:7], v[214:215], v[216:217], v[6:7] op_sel_hi:[0,1,1]
	v_pk_fma_f32 v[8:9], v[214:215], v[218:219], v[8:9] op_sel_hi:[0,1,1]
	v_pk_fma_f32 v[2:3], v[214:215], v[216:217], v[2:3] op_sel:[1,0,0]
	v_pk_fma_f32 v[4:5], v[214:215], v[218:219], v[4:5] op_sel:[1,0,0]
	s_cmpk_lg_i32 s4, 0x4400
	s_cbranch_scc1 .LBB0_644
	s_waitcnt lgkmcnt(0)
	s_add_u32 s4, s12, s0
	s_addc_u32 s5, s13, s1
	v_lshl_add_u64 v[54:55], s[4:5], 0, v[0:1]
	v_lshlrev_b64 v[18:19], 2, v[18:19]
	v_lshl_add_u64 v[54:55], v[54:55], 0, v[18:19]
	global_store_dwordx4 v[54:55], v[14:17], off
	global_store_dwordx4 v[54:55], v[10:13], off offset:256
	global_store_dwordx4 v[54:55], v[6:9], off offset:512
	global_store_dwordx4 v[54:55], v[2:5], off offset:768
	s_barrier
	s_nop 0
	v_pk_mul_f32 v[4:5], v[48:49], v[52:53] op_sel_hi:[1,0]
	v_pk_mul_f32 v[2:3], v[44:45], v[52:53] op_sel_hi:[1,0]
	ds_write_b128 v53, v[2:5]
	v_pk_mul_f32 v[4:5], v[46:47], v[52:53] op_sel_hi:[1,0]
	v_pk_mul_f32 v[2:3], v[40:41], v[52:53] op_sel_hi:[1,0]
	ds_write_b128 v53, v[2:5] offset:16
	v_pk_mul_f32 v[4:5], v[42:43], v[52:53] op_sel_hi:[1,0]
	v_pk_mul_f32 v[2:3], v[36:37], v[52:53] op_sel_hi:[1,0]
	ds_write_b128 v53, v[2:5] offset:32
	v_pk_mul_f32 v[4:5], v[38:39], v[52:53] op_sel_hi:[1,0]
	v_pk_mul_f32 v[2:3], v[34:35], v[52:53] op_sel_hi:[1,0]
	ds_write_b128 v53, v[2:5] offset:48
	s_waitcnt lgkmcnt(0)
	s_barrier
	ds_read_b128 v[2:5], v102
	ds_read_b128 v[6:9], v102 offset:272
	ds_read_b128 v[10:13], v102 offset:544
	ds_read_b128 v[14:17], v102 offset:816
	s_add_u32 s0, s14, s0
	s_addc_u32 s1, s15, s1
	s_waitcnt lgkmcnt(2)
	v_mov_b32_e32 v35, v6
	v_mov_b32_e32 v6, v3
	v_lshl_add_u64 v[36:37], s[0:1], 0, v[0:1]
	v_mov_b32_e32 v34, v2
	s_waitcnt lgkmcnt(1)
	v_mov_b32_e32 v38, v10
	s_waitcnt lgkmcnt(0)
	v_mov_b32_e32 v39, v14
	v_mov_b32_e32 v14, v11
	v_pk_add_f32 v[28:29], v[6:7], v[28:29] neg_lo:[0,1] neg_hi:[0,1]
	v_mov_b32_e32 v2, v4
	v_mov_b32_e32 v3, v8
	v_mov_b32_e32 v6, v12
	v_mov_b32_e32 v7, v16
	v_mov_b32_e32 v8, v5
	v_mov_b32_e32 v16, v13
	v_pk_add_f32 v[32:33], v[34:35], v[32:33] neg_lo:[0,1] neg_hi:[0,1]
	v_pk_add_f32 v[34:35], v[38:39], v[50:51] neg_lo:[0,1] neg_hi:[0,1]
	v_lshl_add_u64 v[18:19], v[36:37], 0, v[18:19]
	v_pk_add_f32 v[30:31], v[14:15], v[30:31] neg_lo:[0,1] neg_hi:[0,1]
	v_pk_add_f32 v[24:25], v[2:3], v[24:25] neg_lo:[0,1] neg_hi:[0,1]
	v_pk_add_f32 v[26:27], v[6:7], v[26:27] neg_lo:[0,1] neg_hi:[0,1]
	v_pk_add_f32 v[2:3], v[8:9], v[22:23] neg_lo:[0,1] neg_hi:[0,1]
	v_pk_add_f32 v[4:5], v[16:17], v[20:21] neg_lo:[0,1] neg_hi:[0,1]
	global_store_dwordx4 v[18:19], v[32:35], off
	global_store_dwordx4 v[18:19], v[28:31], off offset:256
	global_store_dwordx4 v[18:19], v[24:27], off offset:512
	global_store_dwordx4 v[18:19], v[2:5], off offset:768
	s_barrier
	s_mov_b64 s[0:1], 0
